# diff-attention QK^T: S0 chain first with deep K-fragment LDS prefetch (S1 accumulator regs as fragment buffers), P0 g_pre hoist
# speedup vs baseline: 1.0017x; 1.0017x over previous
; template <int KB, bool ROPE, bool AUG, bool QLDS = false>
; __device__ __forceinline__ void qkt(f32x16& p0, f32x16& p1, const char* K_lds, const char* K2_lds, int r32, int hi, const bf16x8* qr, const char* q2l, bf16x8 ka0, bf16x8 ka1, bf16x8 qa) {
;     p0 = f32x16{}; p1 = f32x16{};
;     const char* kb[4];
; #pragma unroll
;     for (int dd = 0; dd < 4; ++dd) kb[dd] = K_lds + KB * SHM_K + KSWZ(r32, (dd * 16 + hi * 8) * 2);
; #pragma unroll
;     for (int d0 = 0; d0 < 8; ++d0) { const char* a = kb[d0 & 3] + (d0 >> 2) * 128;
;         bf16x8 b0 = *reinterpret_cast<const bf16x8*>(a);
;         bf16x8 b1 = *reinterpret_cast<const bf16x8*>(a + 32 * 256);
;         bf16x8 qf; if (QLDS && d0 >= 6) qf = *reinterpret_cast<const bf16x8*>(q2l + (d0 - 6) * 1024); else qf = qr[d0];
;         p0 = __builtin_amdgcn_mfma_f32_32x32x16_bf16(b0, qf, p0, 0, 0, 0);
;         p1 = __builtin_amdgcn_mfma_f32_32x32x16_bf16(b1, qf, p1, 0, 0, 0); }
;     if constexpr (ROPE) {
; #pragma unroll
;         for (int e = 0; e < 4; ++e) { const char* a = K2_lds + KB * SHM_K2 + K2SWZ(r32, (e * 2 + hi) * 16);
;             bf16x8 b0 = *reinterpret_cast<const bf16x8*>(a);
;             bf16x8 b1 = *reinterpret_cast<const bf16x8*>(a + 32 * 128);
;             const bf16x8 q2 = *reinterpret_cast<const bf16x8*>(q2l + e * 1024);
;             p0 = __builtin_amdgcn_mfma_f32_32x32x16_bf16(b0, q2, p0, 0, 0, 0);
;             p1 = __builtin_amdgcn_mfma_f32_32x32x16_bf16(b1, q2, p1, 0, 0, 0); }
;     }
;     if constexpr (AUG) {
;         p0 = __builtin_amdgcn_mfma_f32_32x32x16_bf16(ka0, qa, p0, 0, 0, 0);
;         p1 = __builtin_amdgcn_mfma_f32_32x32x16_bf16(ka1, qa, p1, 0, 0, 0); }
; }
.LBB0_723:
	s_add_u32 s52, s71, s40
	s_addc_u32 s53, s88, 0
	s_add_u32 s54, s89, s40
	s_addc_u32 s55, s92, 0
	v_lshl_add_u64 v[0:1], s[52:53], 0, v[212:213]
	v_lshl_add_u64 v[8:9], s[52:53], 0, v[214:215]
	global_load_dwordx4 v[4:7], v[0:1], off
	s_nop 0
	global_load_dwordx4 v[8:11], v[8:9], off
	v_lshl_add_u64 v[0:1], s[54:55], 0, v[212:213]
	v_lshl_add_u64 v[12:13], s[54:55], 0, v[214:215]
	global_load_dwordx4 v[204:207], v[0:1], off
	s_nop 0
	global_load_dwordx4 v[12:15], v[12:13], off
	s_mov_b64 s[58:59], -1
	s_and_b64 vcc, exec, s[46:47]
	s_cbranch_vccz .LBB0_725
	v_mov_b32_e32 v0, v209
	ds_read_b128 v[128:131], v237
	ds_read_b128 v[148:151], v238
	ds_read_b128 v[152:155], v239
	ds_read_b128 v[156:159], v240
	ds_read_b128 v[246:249], v237 offset:128
	ds_read_b128 v[250:253], v238 offset:128
	ds_read_b128 v[144:147], v237 offset:8192
	s_add_i32 s16, s35, s69
	s_add_i32 s16, s16, -3
	v_cvt_f32_i32_e32 v1, s16
	v_cmp_eq_u32_e32 vcc, 0, v0
	v_mov_b32_e32 v0, s67
	s_waitcnt lgkmcnt(6)
	v_mfma_f32_32x32x16_bf16 v[128:143], v[128:131], v[160:163], 0
	v_lshrrev_b32_e32 v1, 16, v1
	v_cndmask_b32_e32 v30, 0, v1, vcc
	v_cndmask_b32_e32 v1, 0, v233, vcc
	v_cndmask_b32_e32 v31, 0, v234, vcc
	v_cndmask_b32_e32 v0, 0, v0, vcc
	v_mov_b32_e32 v3, v2
	s_mov_b64 s[58:59], 0
	s_waitcnt lgkmcnt(5)
	v_mfma_f32_32x32x16_bf16 v[128:143], v[148:151], v[164:167], v[128:143]
	ds_read_b128 v[148:151], v239 offset:128
	s_waitcnt lgkmcnt(5)
	v_mfma_f32_32x32x16_bf16 v[128:143], v[152:155], v[168:171], v[128:143]
	ds_read_b128 v[152:155], v240 offset:128
	s_waitcnt lgkmcnt(5)
	v_mfma_f32_32x32x16_bf16 v[128:143], v[156:159], v[172:175], v[128:143]
	s_waitcnt lgkmcnt(4)
	v_mfma_f32_32x32x16_bf16 v[128:143], v[246:249], v[176:179], v[128:143]
	ds_read_b128 v[246:249], v238 offset:8192
	s_waitcnt lgkmcnt(4)
	v_mfma_f32_32x32x16_bf16 v[128:143], v[250:253], v[180:183], v[128:143]
	ds_read_b128 v[250:253], v239 offset:8192
	s_waitcnt lgkmcnt(3)
	v_mfma_f32_32x32x16_bf16 v[128:143], v[148:151], v[184:187], v[128:143]
	s_waitcnt lgkmcnt(2)
	v_mfma_f32_32x32x16_bf16 v[128:143], v[152:155], v[188:191], v[128:143]
	v_mfma_f32_32x32x16_bf16 v[144:159], v[144:147], v[160:163], 0
	s_waitcnt lgkmcnt(1)
	v_mfma_f32_32x32x16_bf16 v[144:159], v[246:249], v[164:167], v[144:159]
	ds_read_b128 v[246:249], v240 offset:8192
	s_waitcnt lgkmcnt(1)
	v_mfma_f32_32x32x16_bf16 v[144:159], v[250:253], v[168:171], v[144:159]
	ds_read_b128 v[250:253], v237 offset:8320
	s_waitcnt lgkmcnt(1)
	v_mfma_f32_32x32x16_bf16 v[144:159], v[246:249], v[172:175], v[144:159]
	ds_read_b128 v[246:249], v238 offset:8320
	s_waitcnt lgkmcnt(1)
	v_mfma_f32_32x32x16_bf16 v[144:159], v[250:253], v[176:179], v[144:159]
	ds_read_b128 v[250:253], v239 offset:8320
	s_waitcnt lgkmcnt(1)
	v_mfma_f32_32x32x16_bf16 v[144:159], v[246:249], v[180:183], v[144:159]
	ds_read_b128 v[246:249], v240 offset:8320
	s_waitcnt lgkmcnt(1)
	v_mfma_f32_32x32x16_bf16 v[144:159], v[250:253], v[184:187], v[144:159]
	s_waitcnt lgkmcnt(0)
	v_mfma_f32_32x32x16_bf16 v[144:159], v[246:249], v[188:191], v[144:159]
	v_or_b32_e32 v246, v30, v1
	v_mov_b32_e32 v247, v2
	v_mov_b32_e32 v248, v2
	v_mov_b32_e32 v249, v2
	v_cndmask_b32_e32 v1, 0, v227, vcc
	v_or_b32_e32 v250, v30, v31
	v_mov_b32_e32 v251, v2
	v_mov_b32_e32 v252, v2
	v_mov_b32_e32 v253, v2
	v_mfma_f32_32x32x16_bf16 v[128:143], v[246:249], v[0:3], v[128:143]
	s_nop 0
	v_mfma_f32_32x32x16_bf16 v[144:159], v[250:253], v[0:3], v[144:159]

; template <int KB, bool ROPE, bool AUG, bool QLDS = false>
; __device__ __forceinline__ void qkt(f32x16& p0, f32x16& p1, const char* K_lds, const char* K2_lds, int r32, int hi, const bf16x8* qr, const char* q2l, bf16x8 ka0, bf16x8 ka1, bf16x8 qa) {
;     p0 = f32x16{}; p1 = f32x16{};
;     const char* kb[4];
; #pragma unroll
;     for (int dd = 0; dd < 4; ++dd) kb[dd] = K_lds + KB * SHM_K + KSWZ(r32, (dd * 16 + hi * 8) * 2);
; #pragma unroll
;     for (int d0 = 0; d0 < 8; ++d0) { const char* a = kb[d0 & 3] + (d0 >> 2) * 128;
;         bf16x8 b0 = *reinterpret_cast<const bf16x8*>(a);
;         bf16x8 b1 = *reinterpret_cast<const bf16x8*>(a + 32 * 256);
;         bf16x8 qf; if (QLDS && d0 >= 6) qf = *reinterpret_cast<const bf16x8*>(q2l + (d0 - 6) * 1024); else qf = qr[d0];
;         p0 = __builtin_amdgcn_mfma_f32_32x32x16_bf16(b0, qf, p0, 0, 0, 0);
;         p1 = __builtin_amdgcn_mfma_f32_32x32x16_bf16(b1, qf, p1, 0, 0, 0); }
;     if constexpr (ROPE) {
; #pragma unroll
;         for (int e = 0; e < 4; ++e) { const char* a = K2_lds + KB * SHM_K2 + K2SWZ(r32, (e * 2 + hi) * 16);
;             bf16x8 b0 = *reinterpret_cast<const bf16x8*>(a);
;             bf16x8 b1 = *reinterpret_cast<const bf16x8*>(a + 32 * 128);
;             const bf16x8 q2 = *reinterpret_cast<const bf16x8*>(q2l + e * 1024);
;             p0 = __builtin_amdgcn_mfma_f32_32x32x16_bf16(b0, q2, p0, 0, 0, 0);
;             p1 = __builtin_amdgcn_mfma_f32_32x32x16_bf16(b1, q2, p1, 0, 0, 0); }
;     }
;     if constexpr (AUG) {
;         p0 = __builtin_amdgcn_mfma_f32_32x32x16_bf16(ka0, qa, p0, 0, 0, 0);
;         p1 = __builtin_amdgcn_mfma_f32_32x32x16_bf16(ka1, qa, p1, 0, 0, 0); }
; }
.LBB0_745:
	s_add_u32 s52, s52, 0x4000
	s_addc_u32 s53, s53, 0
	s_add_u32 s54, s54, 0x4000
	s_addc_u32 s55, s55, 0
	v_lshl_add_u64 v[0:1], s[52:53], 0, v[212:213]
	v_lshl_add_u64 v[4:5], s[52:53], 0, v[214:215]
	global_load_dwordx4 v[8:11], v[0:1], off
	global_load_dwordx4 v[12:15], v[4:5], off
	v_lshl_add_u64 v[0:1], s[54:55], 0, v[212:213]
	v_lshl_add_u64 v[4:5], s[54:55], 0, v[214:215]
	global_load_dwordx4 v[204:207], v[0:1], off
	s_nop 0
	global_load_dwordx4 v[4:7], v[4:5], off
	s_mov_b64 s[52:53], -1
	s_and_b64 vcc, exec, s[84:85]
	s_cbranch_vccz .LBB0_747
	v_mov_b32_e32 v0, v209
	ds_read_b128 v[96:99], v241
	ds_read_b128 v[116:119], v242
	ds_read_b128 v[120:123], v243
	ds_read_b128 v[124:127], v244
	ds_read_b128 v[246:249], v241 offset:128
	ds_read_b128 v[250:253], v242 offset:128
	ds_read_b128 v[112:115], v241 offset:8192
	s_add_i32 s17, s35, s69
	s_add_i32 s17, s17, -2
	v_cvt_f32_i32_e32 v1, s17
	v_cmp_eq_u32_e32 vcc, 0, v0
	v_mov_b32_e32 v0, s67
	s_waitcnt lgkmcnt(6)
	v_mfma_f32_32x32x16_bf16 v[96:111], v[96:99], v[160:163], 0
	v_lshrrev_b32_e32 v1, 16, v1
	v_cndmask_b32_e32 v30, 0, v1, vcc
	v_cndmask_b32_e32 v1, 0, v233, vcc
	v_cndmask_b32_e32 v31, 0, v234, vcc
	v_cndmask_b32_e32 v0, 0, v0, vcc
	v_mov_b32_e32 v3, v2
	s_mov_b64 s[52:53], 0
	s_waitcnt lgkmcnt(5)
	v_mfma_f32_32x32x16_bf16 v[96:111], v[116:119], v[164:167], v[96:111]
	ds_read_b128 v[116:119], v243 offset:128
	s_waitcnt lgkmcnt(5)
	v_mfma_f32_32x32x16_bf16 v[96:111], v[120:123], v[168:171], v[96:111]
	ds_read_b128 v[120:123], v244 offset:128
	s_waitcnt lgkmcnt(5)
	v_mfma_f32_32x32x16_bf16 v[96:111], v[124:127], v[172:175], v[96:111]
	s_waitcnt lgkmcnt(4)
	v_mfma_f32_32x32x16_bf16 v[96:111], v[246:249], v[176:179], v[96:111]
	ds_read_b128 v[246:249], v242 offset:8192
	s_waitcnt lgkmcnt(4)
	v_mfma_f32_32x32x16_bf16 v[96:111], v[250:253], v[180:183], v[96:111]
	ds_read_b128 v[250:253], v243 offset:8192
	s_waitcnt lgkmcnt(3)
	v_mfma_f32_32x32x16_bf16 v[96:111], v[116:119], v[184:187], v[96:111]
	s_waitcnt lgkmcnt(2)
	v_mfma_f32_32x32x16_bf16 v[96:111], v[120:123], v[188:191], v[96:111]
	v_mfma_f32_32x32x16_bf16 v[112:127], v[112:115], v[160:163], 0
	s_waitcnt lgkmcnt(1)
	v_mfma_f32_32x32x16_bf16 v[112:127], v[246:249], v[164:167], v[112:127]
	ds_read_b128 v[246:249], v244 offset:8192
	s_waitcnt lgkmcnt(1)
	v_mfma_f32_32x32x16_bf16 v[112:127], v[250:253], v[168:171], v[112:127]
	ds_read_b128 v[250:253], v241 offset:8320
	s_waitcnt lgkmcnt(1)
	v_mfma_f32_32x32x16_bf16 v[112:127], v[246:249], v[172:175], v[112:127]
	ds_read_b128 v[246:249], v242 offset:8320
	s_waitcnt lgkmcnt(1)
	v_mfma_f32_32x32x16_bf16 v[112:127], v[250:253], v[176:179], v[112:127]
	ds_read_b128 v[250:253], v243 offset:8320
	s_waitcnt lgkmcnt(1)
	v_mfma_f32_32x32x16_bf16 v[112:127], v[246:249], v[180:183], v[112:127]
	ds_read_b128 v[246:249], v244 offset:8320
	s_waitcnt lgkmcnt(1)
	v_mfma_f32_32x32x16_bf16 v[112:127], v[250:253], v[184:187], v[112:127]
	s_waitcnt lgkmcnt(0)
	v_mfma_f32_32x32x16_bf16 v[112:127], v[246:249], v[188:191], v[112:127]
	v_or_b32_e32 v246, v30, v1
	v_mov_b32_e32 v247, v2
	v_mov_b32_e32 v248, v2
	v_mov_b32_e32 v249, v2
	v_cndmask_b32_e32 v1, 0, v227, vcc
	v_or_b32_e32 v250, v30, v31
	v_mov_b32_e32 v251, v2
	v_mov_b32_e32 v252, v2
	v_mov_b32_e32 v253, v2
	v_mfma_f32_32x32x16_bf16 v[96:111], v[246:249], v[0:3], v[96:111]
	s_nop 0
	v_mfma_f32_32x32x16_bf16 v[112:127], v[250:253], v[0:3], v[112:127]

; #define lane lane_id()
; __global__ void __launch_bounds__(NWAVES * 64, 2) hybrid_fwd(Args args) {
;     ...
;         float lam;
;         { const float a = lq1[lane] * lk1[lane] + lq1[lane + 64] * lk1[lane + 64], c = lq2[lane] * lk2[lane] + lq2[lane + 64] * lk2[lane + 64];
;           lam = __expf(wave_sum(a)) - __expf(wave_sum(c)) + LAMBDA_INIT; }
;         f32x4 sl0 = *(const f32x4*)(subln + (lane & 31) * 8), sl1 = *(const f32x4*)(subln + (lane & 31) * 8 + 4);
.LBB0_844:
	s_cmp_lt_i32 s30, 6
	s_cselect_b64 s[4:5], -1, 0
	s_and_b64 s[0:1], s[4:5], s[2:3]
	s_andn2_b64 vcc, exec, s[0:1]
	v_mbcnt_lo_u32_b32 v146, -1, 0
	s_cbranch_vccnz .LBB0_848
	s_waitcnt vmcnt(0)
	v_mbcnt_lo_u32_b32 v0, -1, 0
	v_mbcnt_hi_u32_b32 v0, -1, v0
	s_waitcnt lgkmcnt(0)
	v_mbcnt_hi_u32_b32 v12, -1, v146
	v_ashrrev_i32_e32 v1, 31, v0
	v_lshl_add_u64 v[0:1], v[0:1], 2, s[20:21]
	global_load_dword v4, v[0:1], off
	v_mbcnt_lo_u32_b32 v0, -1, 0
	v_mbcnt_hi_u32_b32 v0, -1, v0
	v_and_b32_e32 v13, 64, v12
	v_ashrrev_i32_e32 v1, 31, v0
	v_lshl_add_u64 v[0:1], v[0:1], 2, s[22:23]
	global_load_dword v5, v[0:1], off
	v_mbcnt_lo_u32_b32 v0, -1, 0
	v_mbcnt_hi_u32_b32 v0, -1, v0
	v_xor_b32_e32 v14, 1, v12
	v_ashrrev_i32_e32 v1, 31, v0
	v_lshl_add_u64 v[0:1], v[0:1], 2, s[20:21]
	global_load_dword v6, v[0:1], off offset:256
	v_mbcnt_lo_u32_b32 v0, -1, 0
	v_mbcnt_hi_u32_b32 v0, -1, v0
	v_add_u32_e32 v13, 64, v13
	v_ashrrev_i32_e32 v1, 31, v0
	v_lshl_add_u64 v[0:1], v[0:1], 2, s[22:23]
	global_load_dword v7, v[0:1], off offset:256
	v_mbcnt_lo_u32_b32 v0, -1, 0
	v_mbcnt_hi_u32_b32 v0, -1, v0
	v_cmp_lt_i32_e32 vcc, v14, v13
	v_ashrrev_i32_e32 v1, 31, v0
	v_lshl_add_u64 v[0:1], v[0:1], 2, s[24:25]
	global_load_dword v8, v[0:1], off
	v_mbcnt_lo_u32_b32 v0, -1, 0
	v_mbcnt_hi_u32_b32 v0, -1, v0
	v_cndmask_b32_e32 v14, v12, v14, vcc
	v_ashrrev_i32_e32 v1, 31, v0
	v_lshl_add_u64 v[0:1], v[0:1], 2, s[26:27]
	global_load_dword v9, v[0:1], off
	v_mbcnt_lo_u32_b32 v0, -1, 0
	v_mbcnt_hi_u32_b32 v0, -1, v0
	v_lshlrev_b32_e32 v88, 2, v14
	v_ashrrev_i32_e32 v1, 31, v0
	v_lshl_add_u64 v[0:1], v[0:1], 2, s[24:25]
	global_load_dword v10, v[0:1], off offset:256
	v_mbcnt_lo_u32_b32 v0, -1, 0
	v_mbcnt_hi_u32_b32 v0, -1, v0
	v_xor_b32_e32 v15, 2, v12
	v_ashrrev_i32_e32 v1, 31, v0
	v_lshl_add_u64 v[0:1], v[0:1], 2, s[26:27]
	global_load_dword v11, v[0:1], off offset:256
	v_mbcnt_lo_u32_b32 v0, -1, 0
	v_mbcnt_hi_u32_b32 v0, -1, v0
	v_cmp_lt_i32_e32 vcc, v15, v13
	v_lshlrev_b32_e32 v0, 5, v0
	v_and_b32_e32 v0, 0x3e0, v0
	global_load_dwordx4 v[0:3], v0, s[36:37]
	v_xor_b32_e32 v16, 4, v12
	s_cmpk_gt_i32 s34, 0x3fff
	s_waitcnt vmcnt(5)
	v_mul_f32_e32 v6, v6, v7
	v_fmac_f32_e32 v6, v4, v5
	ds_bpermute_b32 v4, v88, v6
	v_cndmask_b32_e32 v7, v12, v15, vcc
	v_lshlrev_b32_e32 v89, 2, v7
	v_cmp_lt_i32_e32 vcc, v16, v13
	v_xor_b32_e32 v5, 8, v12
	s_waitcnt lgkmcnt(0)
	v_add_f32_e32 v4, v6, v4
	ds_bpermute_b32 v6, v89, v4
	v_cndmask_b32_e32 v7, v12, v16, vcc
	v_lshlrev_b32_e32 v90, 2, v7
	v_cmp_lt_i32_e32 vcc, v5, v13
	s_waitcnt lgkmcnt(0)
	v_add_f32_e32 v4, v4, v6
	ds_bpermute_b32 v6, v90, v4
	v_cndmask_b32_e32 v5, v12, v5, vcc
	v_lshlrev_b32_e32 v91, 2, v5
	s_waitcnt lgkmcnt(0)
	v_add_f32_e32 v4, v4, v6
	s_waitcnt vmcnt(1)
	v_mul_f32_e32 v7, v10, v11
	v_fmac_f32_e32 v7, v8, v9
	ds_bpermute_b32 v8, v88, v7
	ds_bpermute_b32 v6, v91, v4
	s_waitcnt lgkmcnt(1)
	v_add_f32_e32 v5, v7, v8
	ds_bpermute_b32 v7, v89, v5
	s_waitcnt lgkmcnt(1)
	v_add_f32_e32 v4, v4, v6
	v_xor_b32_e32 v8, 16, v12
	v_cmp_lt_i32_e32 vcc, v8, v13
	s_waitcnt lgkmcnt(0)
	v_add_f32_e32 v5, v5, v7
	ds_bpermute_b32 v6, v90, v5
	v_cndmask_b32_e32 v7, v12, v8, vcc
	v_lshlrev_b32_e32 v92, 2, v7
	ds_bpermute_b32 v7, v92, v4
	s_waitcnt lgkmcnt(1)
	v_add_f32_e32 v5, v5, v6
	ds_bpermute_b32 v6, v91, v5
	s_waitcnt lgkmcnt(1)
	v_add_f32_e32 v8, v4, v7
	v_xor_b32_e32 v4, 32, v12
	v_cmp_lt_i32_e32 vcc, v4, v13
	s_waitcnt lgkmcnt(0)
	v_add_f32_e32 v5, v5, v6
	ds_bpermute_b32 v6, v92, v5
	v_cndmask_b32_e32 v4, v12, v4, vcc
	v_lshlrev_b32_e32 v4, 2, v4
	ds_bpermute_b32 v9, v4, v8
	s_waitcnt lgkmcnt(1)
	v_add_f32_e32 v10, v5, v6
	ds_bpermute_b32 v11, v4, v10
	v_mbcnt_lo_u32_b32 v4, -1, 0
	v_mbcnt_hi_u32_b32 v4, -1, v4
	s_cbranch_scc1 .LBB0_848
	v_lshlrev_b32_e32 v4, 5, v4
	v_and_b32_e32 v4, 0x3e0, v4
	global_load_dwordx4 v[4:7], v4, s[36:37] offset:16
	s_waitcnt lgkmcnt(1)
	v_add_f32_e32 v8, v8, v9
	s_waitcnt lgkmcnt(0)
	v_add_f32_e32 v9, v10, v11
	s_waitcnt vmcnt(1)
	v_mov_b32_e32 v82, v1
	v_mov_b32_e32 v83, v3
	v_mov_b32_e32 v1, v2
	v_mul_f32_e32 v2, 0x3fb8aa3b, v8
	v_mul_f32_e32 v3, 0x3fb8aa3b, v9
	v_exp_f32_e32 v2, v2
	v_exp_f32_e32 v3, v3
	s_ashr_i32 s35, s34, 31
	s_ashr_i32 s69, s68, 31
	s_mov_b32 s0, 0x21700000
	v_sub_f32_e32 v2, v2, v3
	v_add_f32_e32 v2, 0x3e4ccccd, v2
	s_mov_b32 s1, 0x1d600000
	s_brev_b32 s11, 28
	s_mov_b32 s20, 0x25800000
	s_mov_b32 s21, 0xffff0000
	v_mov_b32_e32 v93, 0x358637bd
	s_mov_b32 s22, 0xf800000
	v_mov_b32_e32 v94, 0x260
	s_mov_b32 s23, 0x3f4ccccd
	s_movk_i32 s24, 0x7fff
	s_mov_b32 s25, 0x9100000
	s_mov_b32 s26, 0x9101000
	s_lshl_b64 s[6:7], s[34:35], 13
	s_lshl_b64 s[8:9], s[68:69], 13
	s_lshl_b64 s[16:17], s[34:35], 12
	s_lshl_b64 s[18:19], s[68:69], 12
	v_mov_b32_e32 v3, v2
	s_mov_b32 s27, s34
	s_waitcnt vmcnt(0)
	v_mov_b32_e32 v84, v5
	v_mov_b32_e32 v85, v7
	v_mov_b32_e32 v5, v6
; __device__ __forceinline__ unsigned pk2(float lo, float hi) { return f2bf(lo) | (f2bf(hi) << 16); }
; __device__ __forceinline__ float silu(float x) { return x / (1.f + __expf(-x)); }
; #define lane lane_id()
; __global__ void __launch_bounds__(NWAVES * 64, 2) hybrid_fwd(Args args) {
;     ...
;         for (int m = gw; m < MR; m += NGW) {
;             const v4u* p1 = (const v4u*)(O1 + (size_t)m * 2048) + lane; const v4u* p2 = (const v4u*)(O2 + (size_t)m * 2048) + lane;
;             const v4u* pg = (const v4u*)(GD + (size_t)m * 2048) + lane;
;             const v4u* pb = (const v4u*)(OB + (size_t)m * 2048) + lane; const v4u* pm = (const v4u*)(GM + (size_t)m * 2048) + lane;
;             v4u a[4], b[4], gt[4], ab[4], gm[4];
; #pragma unroll
;             for (int j = 0; j < 4; ++j) { a[j] = p1[64 * j]; b[j] = p2[64 * j]; gt[j] = pg[64 * j]; ab[j] = pb[64 * j]; gm[j] = pm[64 * j]; }
;             v4u* po = (v4u*)(MIX + (size_t)m * 4096) + lane;
; #pragma unroll
;             for (int j = 0; j < 4; ++j) { float d[8]; float ss = 0.f;
; #pragma unroll
;                 for (int e = 0; e < 4; ++e) { const float d0 = bflo(a[j][e]) - lam * bflo(b[j][e]), d1 = bfhi(a[j][e]) - lam * bfhi(b[j][e]); d[2 * e] = d0; d[2 * e + 1] = d1; ss += d0 * d0 + d1 * d1; }
;                 ss += __shfl_xor(ss, 1); ss += __shfl_xor(ss, 2); ss += __shfl_xor(ss, 4); ss += __shfl_xor(ss, 8); ss += __shfl_xor(ss, 16);
;                 const float rstd = (1.f - LAMBDA_INIT) / sqrtf(ss * (1.f / 256.f) + RMS_EPS); v4u o;
; #pragma unroll
;                 for (int e = 0; e < 4; ++e) { const f32x4 s4 = (e >> 1) ? sl1 : sl0;
;                     o[e] = pk2(d[2 * e] * rstd * s4[(e & 1) * 2] * silu(bflo(gt[j][e])), d[2 * e + 1] * rstd * s4[(e & 1) * 2 + 1] * silu(bfhi(gt[j][e]))); }
.LBB0_847:
	s_add_u32 s2, s28, s16
	v_mbcnt_lo_u32_b32 v6, -1, 0
	v_mbcnt_hi_u32_b32 v6, -1, v6
	s_addc_u32 s3, s29, s17
	v_mbcnt_lo_u32_b32 v8, -1, 0
	v_mbcnt_hi_u32_b32 v8, -1, v8
	v_mbcnt_lo_u32_b32 v10, -1, 0
	v_mbcnt_hi_u32_b32 v10, -1, v10
	v_ashrrev_i32_e32 v7, 31, v6
	v_ashrrev_i32_e32 v9, 31, v8
	v_lshl_add_u64 v[8:9], v[8:9], 4, s[2:3]
	v_ashrrev_i32_e32 v11, 31, v10
	v_add_co_u32_e32 v8, vcc, s0, v8
	v_lshl_add_u64 v[10:11], v[10:11], 4, s[2:3]
	s_nop 0
	v_addc_co_u32_e32 v9, vcc, 0, v9, vcc
	v_add_co_u32_e32 v10, vcc, s1, v10
	v_lshl_add_u64 v[6:7], v[6:7], 4, s[2:3]
	s_nop 0
	v_addc_co_u32_e32 v11, vcc, 0, v11, vcc
	v_mbcnt_lo_u32_b32 v12, -1, 0
	v_mbcnt_hi_u32_b32 v12, -1, v12
	v_mbcnt_lo_u32_b32 v14, -1, 0
	v_mbcnt_hi_u32_b32 v14, -1, v14
	global_load_dwordx4 v[78:81], v[6:7], off
	global_load_dwordx4 v[96:99], v[8:9], off
	global_load_dwordx4 v[74:77], v[10:11], off
	v_ashrrev_i32_e32 v13, 31, v12
	v_lshl_add_u64 v[12:13], v[12:13], 4, s[2:3]
	v_add_co_u32_e32 v12, vcc, s11, v12
	v_ashrrev_i32_e32 v15, 31, v14
	s_nop 0
	v_addc_co_u32_e32 v13, vcc, 0, v13, vcc
	global_load_dwordx4 v[66:69], v[12:13], off
	v_lshl_add_u64 v[14:15], v[14:15], 4, s[2:3]
	v_add_co_u32_e32 v86, vcc, s20, v14
	s_add_u32 s2, s28, s6
	s_nop 0
	v_addc_co_u32_e32 v87, vcc, 0, v15, vcc
	global_load_dwordx4 v[70:73], v[86:87], off
	global_load_dwordx4 v[58:61], v[6:7], off offset:1024
	global_load_dwordx4 v[62:65], v[8:9], off offset:1024
	global_load_dwordx4 v[54:57], v[10:11], off offset:1024
	global_load_dwordx4 v[46:49], v[12:13], off offset:1024
	global_load_dwordx4 v[50:53], v[86:87], off offset:1024
	global_load_dwordx4 v[38:41], v[6:7], off offset:2048
	global_load_dwordx4 v[42:45], v[8:9], off offset:2048
	global_load_dwordx4 v[34:37], v[10:11], off offset:2048
	global_load_dwordx4 v[26:29], v[12:13], off offset:2048
	global_load_dwordx4 v[30:33], v[86:87], off offset:2048
	global_load_dwordx4 v[18:21], v[6:7], off offset:3072
	global_load_dwordx4 v[22:25], v[8:9], off offset:3072
	global_load_dwordx4 v[14:17], v[10:11], off offset:3072
	s_nop 0
	global_load_dwordx4 v[6:9], v[12:13], off offset:3072
	s_nop 0
	global_load_dwordx4 v[10:13], v[86:87], off offset:3072
	v_mbcnt_lo_u32_b32 v86, -1, 0
	v_mbcnt_hi_u32_b32 v86, -1, v86
	s_addc_u32 s3, s29, s7
	v_ashrrev_i32_e32 v87, 31, v86
	v_lshl_add_u64 v[86:87], v[86:87], 4, s[2:3]
	s_add_i32 s27, s27, s68
	s_add_u32 s6, s6, s8
	s_addc_u32 s7, s7, s9
	s_add_u32 s16, s16, s18
	s_addc_u32 s17, s17, s19
	s_cmpk_lt_i32 s27, 0x4000
	s_waitcnt vmcnt(19)
	v_lshlrev_b32_e32 v105, 16, v79
	s_waitcnt vmcnt(18)
	v_lshlrev_b32_e32 v100, 16, v96
	v_lshlrev_b32_e32 v101, 16, v97
	v_lshlrev_b32_e32 v104, 16, v78
	s_waitcnt vmcnt(17)
	v_lshlrev_b32_e32 v95, 16, v75
	v_lshlrev_b32_e32 v106, 16, v74
	v_pk_fma_f32 v[100:101], v[2:3], v[100:101], v[104:105] neg_lo:[1,0,0] neg_hi:[1,0,0]
	v_mul_f32_e32 v104, 0xbfb8aa3b, v106
	v_and_b32_e32 v107, 0xffff0000, v75
	v_mul_f32_e32 v75, 0xbfb8aa3b, v95
	v_exp_f32_e32 v104, v104
	v_exp_f32_e32 v105, v75
	v_and_b32_e32 v108, 0xffff0000, v74
	v_mul_f32_e32 v74, 0xbfb8aa3b, v108
	v_exp_f32_e32 v74, v74
	v_pk_add_f32 v[104:105], v[104:105], 1.0 op_sel_hi:[1,0]
	v_and_b32_e32 v96, 0xffff0000, v96
	v_div_scale_f32 v75, s[2:3], v105, v105, v95
	v_rcp_f32_e32 v109, v75
	v_and_b32_e32 v97, 0xffff0000, v97
	v_and_b32_e32 v79, 0xffff0000, v79
	v_and_b32_e32 v78, 0xffff0000, v78
	v_fma_f32 v110, -v75, v109, 1.0
	v_fmac_f32_e32 v109, v110, v109
	v_div_scale_f32 v110, vcc, v95, v105, v95
	v_mul_f32_e32 v111, v110, v109
	v_fma_f32 v112, -v75, v111, v110
	v_fmac_f32_e32 v111, v112, v109
	v_fma_f32 v75, -v75, v111, v110
	v_div_fmas_f32 v75, v75, v109, v111
	v_div_fixup_f32 v105, v75, v105, v95
	v_div_scale_f32 v75, s[2:3], v104, v104, v106
	v_rcp_f32_e32 v95, v75
	v_lshlrev_b32_e32 v102, 16, v98
	v_and_b32_e32 v98, 0xffff0000, v98
	v_lshlrev_b32_e32 v103, 16, v99
	v_fma_f32 v109, -v75, v95, 1.0
	v_fmac_f32_e32 v95, v109, v95
	v_div_scale_f32 v109, vcc, v106, v104, v106
	v_mul_f32_e32 v110, v109, v95
	v_fma_f32 v111, -v75, v110, v109
	v_fmac_f32_e32 v110, v111, v95
	v_fma_f32 v75, -v75, v110, v109
	v_div_fmas_f32 v75, v75, v95, v110
	v_div_fixup_f32 v104, v75, v104, v106
	v_mul_f32_e32 v75, 0xbfb8aa3b, v107
	v_exp_f32_e32 v75, v75
	v_and_b32_e32 v99, 0xffff0000, v99
	v_pk_fma_f32 v[78:79], v[2:3], v[96:97], v[78:79] neg_lo:[1,0,0] neg_hi:[1,0,0]
	v_pk_add_f32 v[74:75], v[74:75], 1.0 op_sel_hi:[1,0]
	s_nop 0
	v_div_scale_f32 v95, s[2:3], v75, v75, v107
	v_rcp_f32_e32 v106, v95
	v_pk_mul_f32 v[96:97], v[78:79], v[78:79]
	v_fma_f32 v109, -v95, v106, 1.0
	v_fmac_f32_e32 v106, v109, v106
	v_div_scale_f32 v109, vcc, v107, v75, v107
	v_mul_f32_e32 v110, v109, v106
	v_fma_f32 v111, -v95, v110, v109
	v_fmac_f32_e32 v110, v111, v106
	v_fma_f32 v95, -v95, v110, v109
	v_div_fmas_f32 v95, v95, v106, v110
	v_div_fixup_f32 v75, v95, v75, v107
	v_div_scale_f32 v95, s[2:3], v74, v74, v108
	v_rcp_f32_e32 v106, v95
	v_pk_fma_f32 v[96:97], v[100:101], v[100:101], v[96:97]
	v_fma_f32 v107, -v95, v106, 1.0
	v_fmac_f32_e32 v106, v107, v106
	v_div_scale_f32 v107, vcc, v108, v74, v108
	v_mul_f32_e32 v109, v107, v106
	v_fma_f32 v110, -v95, v109, v107
	v_fmac_f32_e32 v109, v110, v106
	v_fma_f32 v95, -v95, v109, v107
	v_div_fmas_f32 v95, v95, v106, v109
	v_lshlrev_b32_e32 v107, 16, v81
	v_lshlrev_b32_e32 v106, 16, v80
	v_and_b32_e32 v81, 0xffff0000, v81
	v_and_b32_e32 v80, 0xffff0000, v80
	v_pk_fma_f32 v[80:81], v[2:3], v[98:99], v[80:81] neg_lo:[1,0,0] neg_hi:[1,0,0]
	v_pk_fma_f32 v[102:103], v[2:3], v[102:103], v[106:107] neg_lo:[1,0,0] neg_hi:[1,0,0]
	v_pk_mul_f32 v[98:99], v[80:81], v[80:81]
	v_div_fixup_f32 v74, v95, v74, v108
	v_pk_fma_f32 v[98:99], v[102:103], v[102:103], v[98:99]
	v_add_f32_e32 v95, v96, v97
	v_add_f32_e32 v95, v95, v98
	v_add_f32_e32 v95, v95, v99
	ds_bpermute_b32 v96, v88, v95
	s_waitcnt lgkmcnt(0)
; __device__ __forceinline__ unsigned pk2(float lo, float hi) { return f2bf(lo) | (f2bf(hi) << 16); }
; __device__ __forceinline__ float silu(float x) { return x / (1.f + __expf(-x)); }
; __global__ void __launch_bounds__(NWAVES * 64, 2) hybrid_fwd(Args args) {
;     ...
;             for (int j = 0; j < 4; ++j) { float d[8]; float ss = 0.f;
; #pragma unroll
;                 for (int e = 0; e < 4; ++e) { const float d0 = bflo(a[j][e]) - lam * bflo(b[j][e]), d1 = bfhi(a[j][e]) - lam * bfhi(b[j][e]); d[2 * e] = d0; d[2 * e + 1] = d1; ss += d0 * d0 + d1 * d1; }
;                 ss += __shfl_xor(ss, 1); ss += __shfl_xor(ss, 2); ss += __shfl_xor(ss, 4); ss += __shfl_xor(ss, 8); ss += __shfl_xor(ss, 16);
;                 const float rstd = (1.f - LAMBDA_INIT) / sqrtf(ss * (1.f / 256.f) + RMS_EPS); v4u o;
; #pragma unroll
;                 for (int e = 0; e < 4; ++e) { const f32x4 s4 = (e >> 1) ? sl1 : sl0;
;                     o[e] = pk2(d[2 * e] * rstd * s4[(e & 1) * 2] * silu(bflo(gt[j][e])), d[2 * e + 1] * rstd * s4[(e & 1) * 2 + 1] * silu(bfhi(gt[j][e]))); }
;                 po[64 * j] = o;
;                 v4u o2;
; #pragma unroll
;                 for (int e = 0; e < 4; ++e) o2[e] = pk2(bflo(ab[j][e]) * silu(bflo(gm[j][e])), bfhi(ab[j][e]) * silu(bfhi(gm[j][e])));
;                 po[256 + 64 * j] = o2; }
	v_add_f32_e32 v95, v95, v96
	ds_bpermute_b32 v96, v89, v95
	s_waitcnt lgkmcnt(0)
	v_add_f32_e32 v95, v95, v96
	ds_bpermute_b32 v96, v90, v95
	s_waitcnt lgkmcnt(0)
	v_add_f32_e32 v95, v95, v96
	ds_bpermute_b32 v96, v91, v95
	s_waitcnt lgkmcnt(0)
	v_add_f32_e32 v95, v95, v96
	ds_bpermute_b32 v96, v92, v95
	s_waitcnt lgkmcnt(0)
	v_add_f32_e32 v95, v95, v96
	v_fmamk_f32 v95, v95, 0x3b800000, v93
	v_cmp_gt_f32_e32 vcc, s22, v95
	v_mul_f32_e32 v96, 0x4f800000, v95
	s_nop 0
	v_cndmask_b32_e32 v95, v95, v96, vcc
	v_sqrt_f32_e32 v96, v95
	s_nop 0
	v_add_u32_e32 v97, -1, v96
	v_fma_f32 v98, -v97, v96, v95
	v_cmp_ge_f32_e64 s[2:3], 0, v98
	v_add_u32_e32 v98, 1, v96
	s_nop 0
	v_cndmask_b32_e64 v97, v96, v97, s[2:3]
	v_fma_f32 v96, -v98, v96, v95
	v_cmp_lt_f32_e64 s[2:3], 0, v96
	s_nop 1
	v_cndmask_b32_e64 v96, v97, v98, s[2:3]
	v_mul_f32_e32 v97, 0x37800000, v96
	v_cndmask_b32_e32 v96, v96, v97, vcc
	v_cmp_class_f32_e32 vcc, v95, v94
	s_nop 1
	v_cndmask_b32_e32 v95, v96, v95, vcc
	v_div_scale_f32 v96, s[2:3], v95, v95, s23
	v_rcp_f32_e32 v97, v96
	s_nop 0
	v_fma_f32 v98, -v96, v97, 1.0
	v_fmac_f32_e32 v97, v98, v97
	v_div_scale_f32 v98, vcc, s23, v95, s23
	v_mul_f32_e32 v99, v98, v97
	v_fma_f32 v106, -v96, v99, v98
	v_fmac_f32_e32 v99, v106, v97
	v_fma_f32 v96, -v96, v99, v98
	v_div_fmas_f32 v96, v96, v97, v99
	v_div_fixup_f32 v96, v96, v95, s23
	v_pk_mul_f32 v[98:99], v[96:97], v[100:101] op_sel_hi:[0,1]
	v_pk_mul_f32 v[78:79], v[96:97], v[78:79] op_sel_hi:[0,1]
	v_pk_mul_f32 v[98:99], v[0:1], v[98:99]
	v_pk_mul_f32 v[78:79], v[82:83], v[78:79]
	v_lshlrev_b32_e32 v95, 16, v77
	v_lshlrev_b32_e32 v97, 16, v76
	v_pk_mul_f32 v[98:99], v[98:99], v[104:105]
	v_pk_mul_f32 v[74:75], v[78:79], v[74:75]
	v_mul_f32_e32 v78, 0xbfb8aa3b, v97
	v_and_b32_e32 v104, 0xffff0000, v77
	v_mul_f32_e32 v77, 0xbfb8aa3b, v95
	v_exp_f32_e32 v78, v78
	v_exp_f32_e32 v79, v77
	v_pk_mul_f32 v[100:101], v[96:97], v[102:103] op_sel_hi:[0,1]
	v_and_b32_e32 v105, 0xffff0000, v76
	v_mul_f32_e32 v76, 0xbfb8aa3b, v105
	v_pk_add_f32 v[78:79], v[78:79], 1.0 op_sel_hi:[1,0]
	v_exp_f32_e32 v76, v76
	v_div_scale_f32 v77, s[2:3], v79, v79, v95
	v_rcp_f32_e32 v102, v77
	v_pk_mul_f32 v[80:81], v[96:97], v[80:81] op_sel_hi:[0,1]
	v_pk_mul_f32 v[100:101], v[4:5], v[100:101]
	v_pk_mul_f32 v[80:81], v[84:85], v[80:81]
	v_fma_f32 v103, -v77, v102, 1.0
	v_fmac_f32_e32 v102, v103, v102
	v_div_scale_f32 v103, vcc, v95, v79, v95
	v_mul_f32_e32 v106, v103, v102
	v_fma_f32 v107, -v77, v106, v103
	v_fmac_f32_e32 v106, v107, v102
	v_fma_f32 v77, -v77, v106, v103
	v_div_fmas_f32 v77, v77, v102, v106
	v_div_fixup_f32 v79, v77, v79, v95
	v_div_scale_f32 v77, s[2:3], v78, v78, v97
	v_rcp_f32_e32 v95, v77
	s_nop 0
	v_fma_f32 v102, -v77, v95, 1.0
	v_fmac_f32_e32 v95, v102, v95
	v_div_scale_f32 v102, vcc, v97, v78, v97
	v_mul_f32_e32 v103, v102, v95
	v_fma_f32 v106, -v77, v103, v102
	v_fmac_f32_e32 v103, v106, v95
	v_fma_f32 v77, -v77, v103, v102
	v_div_fmas_f32 v77, v77, v95, v103
	v_div_fixup_f32 v78, v77, v78, v97
	v_mul_f32_e32 v77, 0xbfb8aa3b, v104
	v_exp_f32_e32 v77, v77
	v_pk_mul_f32 v[78:79], v[100:101], v[78:79]
	v_pk_add_f32 v[76:77], v[76:77], 1.0 op_sel_hi:[1,0]
	s_nop 0
	v_div_scale_f32 v95, s[2:3], v77, v77, v104
	v_rcp_f32_e32 v96, v95
	s_nop 0
	v_fma_f32 v97, -v95, v96, 1.0
	v_fmac_f32_e32 v96, v97, v96
	v_div_scale_f32 v97, vcc, v104, v77, v104
	v_mul_f32_e32 v100, v97, v96
	v_fma_f32 v101, -v95, v100, v97
	v_fmac_f32_e32 v100, v101, v96
	v_fma_f32 v95, -v95, v100, v97
	v_div_fmas_f32 v95, v95, v96, v100
	v_div_fixup_f32 v77, v95, v77, v104
	v_div_scale_f32 v95, s[2:3], v76, v76, v105
	v_rcp_f32_e32 v96, v95
	s_nop 0
	v_fma_f32 v97, -v95, v96, 1.0
	v_fmac_f32_e32 v96, v97, v96
	v_div_scale_f32 v97, vcc, v105, v76, v105
	v_mul_f32_e32 v100, v97, v96
	v_fma_f32 v101, -v95, v100, v97
	v_fmac_f32_e32 v100, v101, v96
	v_fma_f32 v95, -v95, v100, v97
	v_div_fmas_f32 v95, v95, v96, v100
	v_div_fixup_f32 v76, v95, v76, v105
	v_pk_mul_f32 v[76:77], v[80:81], v[76:77]
	v_bfe_u32 v95, v75, 16, 1
	v_bfe_u32 v80, v77, 16, 1
	v_bfe_u32 v81, v76, 16, 1
	v_add3_u32 v77, v77, v80, s24
	v_bfe_u32 v80, v98, 16, 1
	v_bfe_u32 v96, v74, 16, 1
	v_add3_u32 v76, v76, v81, s24
	v_bfe_u32 v81, v99, 16, 1
	v_add3_u32 v80, v98, v80, s24
	v_add3_u32 v74, v74, v96, s24
	v_add3_u32 v75, v75, v95, s24
	v_bfe_u32 v95, v78, 16, 1
	v_add3_u32 v81, v99, v81, s24
	v_lshrrev_b32_e32 v80, 16, v80
	v_bfe_u32 v96, v79, 16, 1
	v_add3_u32 v78, v78, v95, s24
	v_lshrrev_b32_e32 v81, 16, v81
	v_and_or_b32 v74, v74, s21, v80
	v_add_co_u32_e32 v80, vcc, s25, v86
	v_add3_u32 v79, v79, v96, s24
	v_lshrrev_b32_e32 v78, 16, v78
	v_and_or_b32 v75, v75, s21, v81
	v_addc_co_u32_e32 v81, vcc, 0, v87, vcc
	v_lshrrev_b32_e32 v79, 16, v79
	v_and_or_b32 v76, v76, s21, v78
	v_add_co_u32_e32 v78, vcc, s26, v86
	v_and_or_b32 v77, v77, s21, v79
	s_nop 0
	v_addc_co_u32_e32 v79, vcc, 0, v87, vcc
	s_waitcnt vmcnt(15)
; __device__ __forceinline__ unsigned pk2(float lo, float hi) { return f2bf(lo) | (f2bf(hi) << 16); }
; __device__ __forceinline__ float silu(float x) { return x / (1.f + __expf(-x)); }
; __global__ void __launch_bounds__(NWAVES * 64, 2) hybrid_fwd(Args args) {
;     ...
;             for (int j = 0; j < 4; ++j) { float d[8]; float ss = 0.f;
; #pragma unroll
;                 for (int e = 0; e < 4; ++e) { const float d0 = bflo(a[j][e]) - lam * bflo(b[j][e]), d1 = bfhi(a[j][e]) - lam * bfhi(b[j][e]); d[2 * e] = d0; d[2 * e + 1] = d1; ss += d0 * d0 + d1 * d1; }
;                 ss += __shfl_xor(ss, 1); ss += __shfl_xor(ss, 2); ss += __shfl_xor(ss, 4); ss += __shfl_xor(ss, 8); ss += __shfl_xor(ss, 16);
;                 const float rstd = (1.f - LAMBDA_INIT) / sqrtf(ss * (1.f / 256.f) + RMS_EPS); v4u o;
; #pragma unroll
;                 for (int e = 0; e < 4; ++e) { const f32x4 s4 = (e >> 1) ? sl1 : sl0;
;                     o[e] = pk2(d[2 * e] * rstd * s4[(e & 1) * 2] * silu(bflo(gt[j][e])), d[2 * e + 1] * rstd * s4[(e & 1) * 2 + 1] * silu(bfhi(gt[j][e]))); }
;                 po[64 * j] = o;
;                 v4u o2;
; #pragma unroll
;                 for (int e = 0; e < 4; ++e) o2[e] = pk2(bflo(ab[j][e]) * silu(bflo(gm[j][e])), bfhi(ab[j][e]) * silu(bfhi(gm[j][e])));
;                 po[256 + 64 * j] = o2; }
	v_lshlrev_b32_e32 v86, 16, v71
	v_lshlrev_b32_e32 v87, 16, v70
	global_store_dwordx4 v[78:79], v[74:77], off offset:-4096
	v_and_b32_e32 v95, 0xffff0000, v71
	v_mul_f32_e32 v71, 0xbfb8aa3b, v86
	v_mul_f32_e32 v74, 0xbfb8aa3b, v87
	v_exp_f32_e32 v74, v74
	v_exp_f32_e32 v75, v71
	v_and_b32_e32 v96, 0xffff0000, v70
	v_mul_f32_e32 v70, 0xbfb8aa3b, v96
	v_exp_f32_e32 v70, v70
	v_pk_add_f32 v[74:75], v[74:75], 1.0 op_sel_hi:[1,0]
	v_lshlrev_b32_e32 v77, 16, v67
	v_div_scale_f32 v71, s[2:3], v75, v75, v86
	v_rcp_f32_e32 v97, v71
	v_lshlrev_b32_e32 v76, 16, v66
	v_and_b32_e32 v67, 0xffff0000, v67
	v_and_b32_e32 v66, 0xffff0000, v66
	v_fma_f32 v98, -v71, v97, 1.0
	v_fmac_f32_e32 v97, v98, v97
	v_div_scale_f32 v98, vcc, v86, v75, v86
	v_mul_f32_e32 v99, v98, v97
	v_fma_f32 v100, -v71, v99, v98
	v_fmac_f32_e32 v99, v100, v97
	v_fma_f32 v71, -v71, v99, v98
	v_div_fmas_f32 v71, v71, v97, v99
	v_div_fixup_f32 v75, v71, v75, v86
	v_div_scale_f32 v71, s[2:3], v74, v74, v87
	v_rcp_f32_e32 v86, v71
	s_nop 0
	v_fma_f32 v97, -v71, v86, 1.0
	v_fmac_f32_e32 v86, v97, v86
	v_div_scale_f32 v97, vcc, v87, v74, v87
	v_mul_f32_e32 v98, v97, v86
	v_fma_f32 v99, -v71, v98, v97
	v_fmac_f32_e32 v98, v99, v86
	v_fma_f32 v71, -v71, v98, v97
	v_div_fmas_f32 v71, v71, v86, v98
	v_div_fixup_f32 v74, v71, v74, v87
	v_mul_f32_e32 v71, 0xbfb8aa3b, v95
	v_exp_f32_e32 v71, v71
	v_pk_mul_f32 v[74:75], v[74:75], v[76:77]
	v_pk_add_f32 v[70:71], v[70:71], 1.0 op_sel_hi:[1,0]
	s_nop 0
	v_div_scale_f32 v76, s[2:3], v71, v71, v95
	v_rcp_f32_e32 v77, v76
	s_nop 0
	v_fma_f32 v86, -v76, v77, 1.0
	v_fmac_f32_e32 v77, v86, v77
	v_div_scale_f32 v86, vcc, v95, v71, v95
	v_mul_f32_e32 v87, v86, v77
	v_fma_f32 v97, -v76, v87, v86
	v_fmac_f32_e32 v87, v97, v77
	v_fma_f32 v76, -v76, v87, v86
	v_div_fmas_f32 v76, v76, v77, v87
	v_div_fixup_f32 v71, v76, v71, v95
	v_div_scale_f32 v76, s[2:3], v70, v70, v96
	v_rcp_f32_e32 v77, v76
	s_nop 0
	v_fma_f32 v86, -v76, v77, 1.0
	v_fmac_f32_e32 v77, v86, v77
	v_div_scale_f32 v86, vcc, v96, v70, v96
	v_mul_f32_e32 v87, v86, v77
	v_fma_f32 v95, -v76, v87, v86
	v_fmac_f32_e32 v87, v95, v77
	v_fma_f32 v76, -v76, v87, v86
	v_div_fmas_f32 v76, v76, v77, v87
	v_div_fixup_f32 v70, v76, v70, v96
	v_and_b32_e32 v96, 0xffff0000, v72
	v_pk_mul_f32 v[66:67], v[70:71], v[66:67]
	v_lshlrev_b32_e32 v86, 16, v73
	v_lshlrev_b32_e32 v87, 16, v72
	v_mul_f32_e32 v71, 0xbfb8aa3b, v96
	v_mul_f32_e32 v70, 0xbfb8aa3b, v87
	v_exp_f32_e32 v72, v71
	v_mul_f32_e32 v71, 0xbfb8aa3b, v86
	v_exp_f32_e32 v70, v70
	v_exp_f32_e32 v71, v71
	v_and_b32_e32 v95, 0xffff0000, v73
	v_lshlrev_b32_e32 v77, 16, v69
	v_lshlrev_b32_e32 v76, 16, v68
	v_pk_add_f32 v[70:71], v[70:71], 1.0 op_sel_hi:[1,0]
	v_and_b32_e32 v69, 0xffff0000, v69
	v_div_scale_f32 v73, s[2:3], v71, v71, v86
	v_rcp_f32_e32 v97, v73
	v_and_b32_e32 v68, 0xffff0000, v68
	v_fma_f32 v98, -v73, v97, 1.0
	v_fmac_f32_e32 v97, v98, v97
	v_div_scale_f32 v98, vcc, v86, v71, v86
	v_mul_f32_e32 v99, v98, v97
	v_fma_f32 v100, -v73, v99, v98
	v_fmac_f32_e32 v99, v100, v97
	v_fma_f32 v73, -v73, v99, v98
	v_div_fmas_f32 v73, v73, v97, v99
	v_div_fixup_f32 v71, v73, v71, v86
	v_div_scale_f32 v73, s[2:3], v70, v70, v87
	v_rcp_f32_e32 v86, v73
	s_nop 0
	v_fma_f32 v97, -v73, v86, 1.0
	v_fmac_f32_e32 v86, v97, v86
	v_div_scale_f32 v97, vcc, v87, v70, v87
	v_mul_f32_e32 v98, v97, v86
	v_fma_f32 v99, -v73, v98, v97
	v_fmac_f32_e32 v98, v99, v86
	v_fma_f32 v73, -v73, v98, v97
	v_div_fmas_f32 v73, v73, v86, v98
	v_div_fixup_f32 v70, v73, v70, v87
	v_mul_f32_e32 v73, 0xbfb8aa3b, v95
	v_exp_f32_e32 v73, v73
	v_pk_mul_f32 v[70:71], v[70:71], v[76:77]
	v_pk_add_f32 v[72:73], v[72:73], 1.0 op_sel_hi:[1,0]
	s_nop 0
	v_div_scale_f32 v76, s[2:3], v73, v73, v95
	v_rcp_f32_e32 v77, v76
	s_nop 0
	v_fma_f32 v86, -v76, v77, 1.0
	v_fmac_f32_e32 v77, v86, v77
	v_div_scale_f32 v86, vcc, v95, v73, v95
	v_mul_f32_e32 v87, v86, v77
	v_fma_f32 v97, -v76, v87, v86
	v_fmac_f32_e32 v87, v97, v77
	v_fma_f32 v76, -v76, v87, v86
	v_div_fmas_f32 v76, v76, v77, v87
	v_div_fixup_f32 v73, v76, v73, v95
	v_div_scale_f32 v76, s[2:3], v72, v72, v96
	v_rcp_f32_e32 v77, v76
	s_nop 0
	v_fma_f32 v86, -v76, v77, 1.0
	v_fmac_f32_e32 v77, v86, v77
	v_div_scale_f32 v86, vcc, v96, v72, v96
	v_mul_f32_e32 v87, v86, v77
	v_fma_f32 v95, -v76, v87, v86
	v_fmac_f32_e32 v87, v95, v77
	v_fma_f32 v76, -v76, v87, v86
	v_div_fmas_f32 v76, v76, v77, v87
	v_div_fixup_f32 v72, v76, v72, v96
	v_pk_mul_f32 v[68:69], v[72:73], v[68:69]
	v_bfe_u32 v76, v67, 16, 1
	v_bfe_u32 v72, v69, 16, 1
	v_bfe_u32 v73, v68, 16, 1
	v_bfe_u32 v77, v66, 16, 1
	v_add3_u32 v66, v66, v77, s24
	v_add3_u32 v67, v67, v76, s24
	v_add3_u32 v68, v68, v73, s24
	v_add3_u32 v69, v69, v72, s24
	v_bfe_u32 v72, v74, 16, 1
	v_bfe_u32 v73, v75, 16, 1
	v_bfe_u32 v76, v70, 16, 1
	v_bfe_u32 v77, v71, 16, 1
	v_add3_u32 v71, v71, v77, s24
	v_add3_u32 v70, v70, v76, s24
	v_add3_u32 v73, v75, v73, s24
	v_add3_u32 v72, v74, v72, s24
	v_lshrrev_b32_e32 v72, 16, v72
	v_lshrrev_b32_e32 v73, 16, v73
	v_lshrrev_b32_e32 v70, 16, v70
	v_lshrrev_b32_e32 v71, 16, v71
	v_and_or_b32 v69, v69, s21, v71
	v_and_or_b32 v68, v68, s21, v70
	v_and_or_b32 v67, v67, s21, v73
	v_and_or_b32 v66, v66, s21, v72
	s_waitcnt vmcnt(13)
; __device__ __forceinline__ unsigned pk2(float lo, float hi) { return f2bf(lo) | (f2bf(hi) << 16); }
; __device__ __forceinline__ float silu(float x) { return x / (1.f + __expf(-x)); }
; __global__ void __launch_bounds__(NWAVES * 64, 2) hybrid_fwd(Args args) {
;     ...
;             for (int j = 0; j < 4; ++j) { float d[8]; float ss = 0.f;
; #pragma unroll
;                 for (int e = 0; e < 4; ++e) { const float d0 = bflo(a[j][e]) - lam * bflo(b[j][e]), d1 = bfhi(a[j][e]) - lam * bfhi(b[j][e]); d[2 * e] = d0; d[2 * e + 1] = d1; ss += d0 * d0 + d1 * d1; }
;                 ss += __shfl_xor(ss, 1); ss += __shfl_xor(ss, 2); ss += __shfl_xor(ss, 4); ss += __shfl_xor(ss, 8); ss += __shfl_xor(ss, 16);
;                 const float rstd = (1.f - LAMBDA_INIT) / sqrtf(ss * (1.f / 256.f) + RMS_EPS); v4u o;
; #pragma unroll
;                 for (int e = 0; e < 4; ++e) { const f32x4 s4 = (e >> 1) ? sl1 : sl0;
;                     o[e] = pk2(d[2 * e] * rstd * s4[(e & 1) * 2] * silu(bflo(gt[j][e])), d[2 * e + 1] * rstd * s4[(e & 1) * 2 + 1] * silu(bfhi(gt[j][e]))); }
;                 po[64 * j] = o;
;                 v4u o2;
; #pragma unroll
;                 for (int e = 0; e < 4; ++e) o2[e] = pk2(bflo(ab[j][e]) * silu(bflo(gm[j][e])), bfhi(ab[j][e]) * silu(bfhi(gm[j][e])));
;                 po[256 + 64 * j] = o2; }
	v_and_b32_e32 v76, 0xffff0000, v54
	global_store_dwordx4 v[78:79], v[66:69], off
	v_lshlrev_b32_e32 v70, 16, v62
	v_lshlrev_b32_e32 v71, 16, v63
	v_and_b32_e32 v68, 0xffff0000, v62
	v_and_b32_e32 v69, 0xffff0000, v63
	v_lshlrev_b32_e32 v66, 16, v64
	v_and_b32_e32 v62, 0xffff0000, v64
	v_lshlrev_b32_e32 v67, 16, v65
	v_and_b32_e32 v63, 0xffff0000, v65
	v_lshlrev_b32_e32 v65, 16, v59
	v_lshlrev_b32_e32 v64, 16, v58
	v_lshlrev_b32_e32 v73, 16, v55
	v_lshlrev_b32_e32 v74, 16, v54
	v_mul_f32_e32 v54, 0xbfb8aa3b, v76
	v_pk_fma_f32 v[64:65], v[2:3], v[70:71], v[64:65] neg_lo:[1,0,0] neg_hi:[1,0,0]
	v_mul_f32_e32 v70, 0xbfb8aa3b, v74
	v_exp_f32_e32 v72, v54
	v_mul_f32_e32 v54, 0xbfb8aa3b, v73
	v_exp_f32_e32 v70, v70
	v_exp_f32_e32 v71, v54
	v_and_b32_e32 v75, 0xffff0000, v55
	v_and_b32_e32 v59, 0xffff0000, v59
	v_and_b32_e32 v58, 0xffff0000, v58
	v_pk_add_f32 v[54:55], v[70:71], 1.0 op_sel_hi:[1,0]
	v_pk_fma_f32 v[58:59], v[2:3], v[68:69], v[58:59] neg_lo:[1,0,0] neg_hi:[1,0,0]
	v_div_scale_f32 v70, s[2:3], v55, v55, v73
	v_rcp_f32_e32 v71, v70
	v_pk_mul_f32 v[68:69], v[58:59], v[58:59]
	v_fma_f32 v77, -v70, v71, 1.0
	v_fmac_f32_e32 v71, v77, v71
	v_div_scale_f32 v77, vcc, v73, v55, v73
	v_mul_f32_e32 v86, v77, v71
	v_fma_f32 v87, -v70, v86, v77
	v_fmac_f32_e32 v86, v87, v71
	v_fma_f32 v70, -v70, v86, v77
	v_div_fmas_f32 v70, v70, v71, v86
	v_div_fixup_f32 v55, v70, v55, v73
	v_div_scale_f32 v70, s[2:3], v54, v54, v74
	v_rcp_f32_e32 v71, v70
	v_pk_fma_f32 v[68:69], v[64:65], v[64:65], v[68:69]
	v_fma_f32 v73, -v70, v71, 1.0
	v_fmac_f32_e32 v71, v73, v71
	v_div_scale_f32 v73, vcc, v74, v54, v74
	v_mul_f32_e32 v77, v73, v71
	v_fma_f32 v86, -v70, v77, v73
	v_fmac_f32_e32 v77, v86, v71
	v_fma_f32 v70, -v70, v77, v73
	v_div_fmas_f32 v70, v70, v71, v77
	v_div_fixup_f32 v54, v70, v54, v74
	v_mul_f32_e32 v70, 0xbfb8aa3b, v75
	v_exp_f32_e32 v73, v70
	v_add_f32_e32 v68, v68, v69
	v_pk_add_f32 v[70:71], v[72:73], 1.0 op_sel_hi:[1,0]
	s_nop 0
	v_div_scale_f32 v72, s[2:3], v71, v71, v75
	v_rcp_f32_e32 v73, v72
	s_nop 0
	v_fma_f32 v74, -v72, v73, 1.0
	v_fmac_f32_e32 v73, v74, v73
	v_div_scale_f32 v74, vcc, v75, v71, v75
	v_mul_f32_e32 v77, v74, v73
	v_fma_f32 v86, -v72, v77, v74
	v_fmac_f32_e32 v77, v86, v73
	v_fma_f32 v72, -v72, v77, v74
	v_div_fmas_f32 v72, v72, v73, v77
	v_div_fixup_f32 v71, v72, v71, v75
	v_div_scale_f32 v72, s[2:3], v70, v70, v76
	v_rcp_f32_e32 v73, v72
	s_nop 0
	v_fma_f32 v74, -v72, v73, 1.0
	v_fmac_f32_e32 v73, v74, v73
	v_div_scale_f32 v74, vcc, v76, v70, v76
	v_mul_f32_e32 v75, v74, v73
	v_fma_f32 v77, -v72, v75, v74
	v_fmac_f32_e32 v75, v77, v73
	v_fma_f32 v72, -v72, v75, v74
	v_div_fmas_f32 v72, v72, v73, v75
	v_div_fixup_f32 v70, v72, v70, v76
	v_lshlrev_b32_e32 v73, 16, v61
	v_lshlrev_b32_e32 v72, 16, v60
	v_and_b32_e32 v61, 0xffff0000, v61
	v_and_b32_e32 v60, 0xffff0000, v60
	v_pk_fma_f32 v[60:61], v[2:3], v[62:63], v[60:61] neg_lo:[1,0,0] neg_hi:[1,0,0]
	v_pk_fma_f32 v[66:67], v[2:3], v[66:67], v[72:73] neg_lo:[1,0,0] neg_hi:[1,0,0]
	v_pk_mul_f32 v[62:63], v[60:61], v[60:61]
	s_nop 0
	v_pk_fma_f32 v[62:63], v[66:67], v[66:67], v[62:63]
	s_nop 0
	v_add_f32_e32 v62, v68, v62
	v_add_f32_e32 v62, v62, v63
	ds_bpermute_b32 v63, v88, v62
	s_waitcnt lgkmcnt(0)
	v_add_f32_e32 v62, v62, v63
	ds_bpermute_b32 v63, v89, v62
	s_waitcnt lgkmcnt(0)
	v_add_f32_e32 v62, v62, v63
	ds_bpermute_b32 v63, v90, v62
	s_waitcnt lgkmcnt(0)
	v_add_f32_e32 v62, v62, v63
	ds_bpermute_b32 v63, v91, v62
	s_waitcnt lgkmcnt(0)
	v_add_f32_e32 v62, v62, v63
	ds_bpermute_b32 v63, v92, v62
	s_waitcnt lgkmcnt(0)
	v_add_f32_e32 v62, v62, v63
	v_fmamk_f32 v62, v62, 0x3b800000, v93
	v_cmp_gt_f32_e32 vcc, s22, v62
	v_mul_f32_e32 v63, 0x4f800000, v62
	s_nop 0
	v_cndmask_b32_e32 v62, v62, v63, vcc
	v_sqrt_f32_e32 v63, v62
	s_nop 0
	v_add_u32_e32 v68, -1, v63
	v_fma_f32 v69, -v68, v63, v62
	v_cmp_ge_f32_e64 s[2:3], 0, v69
	v_add_u32_e32 v69, 1, v63
	s_nop 0
	v_cndmask_b32_e64 v68, v63, v68, s[2:3]
	v_fma_f32 v63, -v69, v63, v62
	v_cmp_lt_f32_e64 s[2:3], 0, v63
	s_nop 1
	v_cndmask_b32_e64 v63, v68, v69, s[2:3]
	v_mul_f32_e32 v68, 0x37800000, v63
	v_cndmask_b32_e32 v63, v63, v68, vcc
	v_cmp_class_f32_e32 vcc, v62, v94
	s_nop 1
	v_cndmask_b32_e32 v62, v63, v62, vcc
	v_div_scale_f32 v63, s[2:3], v62, v62, s23
	v_rcp_f32_e32 v68, v63
	s_nop 0
	v_fma_f32 v69, -v63, v68, 1.0
	v_fmac_f32_e32 v68, v69, v68
	v_div_scale_f32 v69, vcc, s23, v62, s23
	v_mul_f32_e32 v72, v69, v68
	v_fma_f32 v73, -v63, v72, v69
	v_fmac_f32_e32 v72, v73, v68
	v_fma_f32 v63, -v63, v72, v69
	v_div_fmas_f32 v63, v63, v68, v72
	v_div_fixup_f32 v62, v63, v62, s23
	v_pk_mul_f32 v[64:65], v[62:63], v[64:65] op_sel_hi:[0,1]
	v_pk_mul_f32 v[64:65], v[0:1], v[64:65]
	v_pk_mul_f32 v[58:59], v[62:63], v[58:59] op_sel_hi:[0,1]
	v_lshlrev_b32_e32 v63, 16, v57
	v_lshlrev_b32_e32 v68, 16, v56
	v_pk_mul_f32 v[54:55], v[64:65], v[54:55]
	v_mul_f32_e32 v64, 0xbfb8aa3b, v68
	v_and_b32_e32 v69, 0xffff0000, v57
	v_mul_f32_e32 v57, 0xbfb8aa3b, v63
	v_exp_f32_e32 v64, v64
	v_exp_f32_e32 v65, v57
	v_pk_mul_f32 v[58:59], v[82:83], v[58:59]
	v_pk_mul_f32 v[66:67], v[62:63], v[66:67] op_sel_hi:[0,1]
	v_pk_mul_f32 v[58:59], v[58:59], v[70:71]
	v_pk_add_f32 v[64:65], v[64:65], 1.0 op_sel_hi:[1,0]
	v_and_b32_e32 v70, 0xffff0000, v56
	v_div_scale_f32 v57, s[2:3], v65, v65, v63
	v_rcp_f32_e32 v71, v57
	v_mul_f32_e32 v56, 0xbfb8aa3b, v70
	v_exp_f32_e32 v56, v56
	v_pk_mul_f32 v[66:67], v[4:5], v[66:67]
	v_fma_f32 v72, -v57, v71, 1.0
	v_fmac_f32_e32 v71, v72, v71
	v_div_scale_f32 v72, vcc, v63, v65, v63
	v_mul_f32_e32 v73, v72, v71
	v_fma_f32 v74, -v57, v73, v72
	v_fmac_f32_e32 v73, v74, v71
	v_fma_f32 v57, -v57, v73, v72
; __device__ __forceinline__ unsigned pk2(float lo, float hi) { return f2bf(lo) | (f2bf(hi) << 16); }
; __device__ __forceinline__ float silu(float x) { return x / (1.f + __expf(-x)); }
; __global__ void __launch_bounds__(NWAVES * 64, 2) hybrid_fwd(Args args) {
;     ...
;             for (int j = 0; j < 4; ++j) { float d[8]; float ss = 0.f;
; #pragma unroll
;                 for (int e = 0; e < 4; ++e) { const float d0 = bflo(a[j][e]) - lam * bflo(b[j][e]), d1 = bfhi(a[j][e]) - lam * bfhi(b[j][e]); d[2 * e] = d0; d[2 * e + 1] = d1; ss += d0 * d0 + d1 * d1; }
;                 ss += __shfl_xor(ss, 1); ss += __shfl_xor(ss, 2); ss += __shfl_xor(ss, 4); ss += __shfl_xor(ss, 8); ss += __shfl_xor(ss, 16);
;                 const float rstd = (1.f - LAMBDA_INIT) / sqrtf(ss * (1.f / 256.f) + RMS_EPS); v4u o;
; #pragma unroll
;                 for (int e = 0; e < 4; ++e) { const f32x4 s4 = (e >> 1) ? sl1 : sl0;
;                     o[e] = pk2(d[2 * e] * rstd * s4[(e & 1) * 2] * silu(bflo(gt[j][e])), d[2 * e + 1] * rstd * s4[(e & 1) * 2 + 1] * silu(bfhi(gt[j][e]))); }
;                 po[64 * j] = o;
;                 v4u o2;
; #pragma unroll
;                 for (int e = 0; e < 4; ++e) o2[e] = pk2(bflo(ab[j][e]) * silu(bflo(gm[j][e])), bfhi(ab[j][e]) * silu(bfhi(gm[j][e])));
;                 po[256 + 64 * j] = o2; }
	v_div_fmas_f32 v57, v57, v71, v73
	v_div_fixup_f32 v65, v57, v65, v63
	v_div_scale_f32 v57, s[2:3], v64, v64, v68
	v_rcp_f32_e32 v63, v57
	s_nop 0
	v_fma_f32 v71, -v57, v63, 1.0
	v_fmac_f32_e32 v63, v71, v63
	v_div_scale_f32 v71, vcc, v68, v64, v68
	v_mul_f32_e32 v72, v71, v63
	v_fma_f32 v73, -v57, v72, v71
	v_fmac_f32_e32 v72, v73, v63
	v_fma_f32 v57, -v57, v72, v71
	v_div_fmas_f32 v57, v57, v63, v72
	v_div_fixup_f32 v64, v57, v64, v68
	v_mul_f32_e32 v57, 0xbfb8aa3b, v69
	v_exp_f32_e32 v57, v57
	v_pk_mul_f32 v[60:61], v[62:63], v[60:61] op_sel_hi:[0,1]
	v_pk_mul_f32 v[64:65], v[66:67], v[64:65]
	v_pk_mul_f32 v[60:61], v[84:85], v[60:61]
	v_pk_add_f32 v[56:57], v[56:57], 1.0 op_sel_hi:[1,0]
	s_nop 0
	v_div_scale_f32 v62, s[2:3], v57, v57, v69
	v_rcp_f32_e32 v63, v62
	s_nop 0
	v_fma_f32 v66, -v62, v63, 1.0
	v_fmac_f32_e32 v63, v66, v63
	v_div_scale_f32 v66, vcc, v69, v57, v69
	v_mul_f32_e32 v67, v66, v63
	v_fma_f32 v68, -v62, v67, v66
	v_fmac_f32_e32 v67, v68, v63
	v_fma_f32 v62, -v62, v67, v66
	v_div_fmas_f32 v62, v62, v63, v67
	v_div_fixup_f32 v57, v62, v57, v69
	v_div_scale_f32 v62, s[2:3], v56, v56, v70
	v_rcp_f32_e32 v63, v62
	s_nop 0
	v_fma_f32 v66, -v62, v63, 1.0
	v_fmac_f32_e32 v63, v66, v63
	v_div_scale_f32 v66, vcc, v70, v56, v70
	v_mul_f32_e32 v67, v66, v63
	v_fma_f32 v68, -v62, v67, v66
	v_fmac_f32_e32 v67, v68, v63
	v_fma_f32 v62, -v62, v67, v66
	v_div_fmas_f32 v62, v62, v63, v67
	v_div_fixup_f32 v56, v62, v56, v70
	v_pk_mul_f32 v[56:57], v[60:61], v[56:57]
	v_bfe_u32 v62, v59, 16, 1
	v_bfe_u32 v60, v57, 16, 1
	v_bfe_u32 v61, v56, 16, 1
	v_bfe_u32 v63, v58, 16, 1
	v_add3_u32 v58, v58, v63, s24
	v_add3_u32 v59, v59, v62, s24
	v_add3_u32 v56, v56, v61, s24
	v_add3_u32 v57, v57, v60, s24
	v_bfe_u32 v60, v54, 16, 1
	v_bfe_u32 v61, v55, 16, 1
	v_bfe_u32 v62, v64, 16, 1
	v_bfe_u32 v63, v65, 16, 1
	v_add3_u32 v63, v65, v63, s24
	v_add3_u32 v62, v64, v62, s24
	v_add3_u32 v55, v55, v61, s24
	v_add3_u32 v54, v54, v60, s24
	v_lshrrev_b32_e32 v54, 16, v54
	v_lshrrev_b32_e32 v55, 16, v55
	v_lshrrev_b32_e32 v60, 16, v62
	v_lshrrev_b32_e32 v61, 16, v63
	v_and_or_b32 v57, v57, s21, v61
	v_and_or_b32 v56, v56, s21, v60
	v_and_or_b32 v55, v59, s21, v55
	v_and_or_b32 v54, v58, s21, v54
	s_waitcnt vmcnt(12)
	v_lshlrev_b32_e32 v58, 16, v51
	v_lshlrev_b32_e32 v59, 16, v50
	global_store_dwordx4 v[80:81], v[54:57], off offset:1024
	v_and_b32_e32 v60, 0xffff0000, v51
	v_mul_f32_e32 v51, 0xbfb8aa3b, v58
	v_mul_f32_e32 v54, 0xbfb8aa3b, v59
	v_exp_f32_e32 v54, v54
	v_exp_f32_e32 v55, v51
	v_and_b32_e32 v61, 0xffff0000, v50
	v_mul_f32_e32 v50, 0xbfb8aa3b, v61
	v_exp_f32_e32 v50, v50
	v_pk_add_f32 v[54:55], v[54:55], 1.0 op_sel_hi:[1,0]
	v_lshlrev_b32_e32 v57, 16, v47
	v_div_scale_f32 v51, s[2:3], v55, v55, v58
	v_rcp_f32_e32 v62, v51
	v_lshlrev_b32_e32 v56, 16, v46
	v_and_b32_e32 v47, 0xffff0000, v47
	v_and_b32_e32 v46, 0xffff0000, v46
	v_fma_f32 v63, -v51, v62, 1.0
	v_fmac_f32_e32 v62, v63, v62
	v_div_scale_f32 v63, vcc, v58, v55, v58
	v_mul_f32_e32 v64, v63, v62
	v_fma_f32 v65, -v51, v64, v63
	v_fmac_f32_e32 v64, v65, v62
	v_fma_f32 v51, -v51, v64, v63
	v_div_fmas_f32 v51, v51, v62, v64
	v_div_fixup_f32 v55, v51, v55, v58
	v_div_scale_f32 v51, s[2:3], v54, v54, v59
	v_rcp_f32_e32 v58, v51
	s_nop 0
	v_fma_f32 v62, -v51, v58, 1.0
	v_fmac_f32_e32 v58, v62, v58
	v_div_scale_f32 v62, vcc, v59, v54, v59
	v_mul_f32_e32 v63, v62, v58
	v_fma_f32 v64, -v51, v63, v62
	v_fmac_f32_e32 v63, v64, v58
	v_fma_f32 v51, -v51, v63, v62
	v_div_fmas_f32 v51, v51, v58, v63
	v_div_fixup_f32 v54, v51, v54, v59
	v_mul_f32_e32 v51, 0xbfb8aa3b, v60
	v_exp_f32_e32 v51, v51
	v_pk_mul_f32 v[54:55], v[54:55], v[56:57]
	v_pk_add_f32 v[50:51], v[50:51], 1.0 op_sel_hi:[1,0]
	s_nop 0
	v_div_scale_f32 v56, s[2:3], v51, v51, v60
	v_rcp_f32_e32 v57, v56
	s_nop 0
	v_fma_f32 v58, -v56, v57, 1.0
	v_fmac_f32_e32 v57, v58, v57
	v_div_scale_f32 v58, vcc, v60, v51, v60
	v_mul_f32_e32 v59, v58, v57
	v_fma_f32 v62, -v56, v59, v58
	v_fmac_f32_e32 v59, v62, v57
	v_fma_f32 v56, -v56, v59, v58
	v_div_fmas_f32 v56, v56, v57, v59
	v_div_fixup_f32 v51, v56, v51, v60
	v_div_scale_f32 v56, s[2:3], v50, v50, v61
	v_rcp_f32_e32 v57, v56
	s_nop 0
	v_fma_f32 v58, -v56, v57, 1.0
	v_fmac_f32_e32 v57, v58, v57
	v_div_scale_f32 v58, vcc, v61, v50, v61
	v_mul_f32_e32 v59, v58, v57
	v_fma_f32 v60, -v56, v59, v58
	v_fmac_f32_e32 v59, v60, v57
	v_fma_f32 v56, -v56, v59, v58
	v_div_fmas_f32 v56, v56, v57, v59
	v_div_fixup_f32 v50, v56, v50, v61
	v_and_b32_e32 v61, 0xffff0000, v52
	v_pk_mul_f32 v[46:47], v[50:51], v[46:47]
	v_lshlrev_b32_e32 v58, 16, v53
	v_lshlrev_b32_e32 v59, 16, v52
	v_mul_f32_e32 v51, 0xbfb8aa3b, v61
	v_mul_f32_e32 v50, 0xbfb8aa3b, v59
	v_exp_f32_e32 v52, v51
	v_mul_f32_e32 v51, 0xbfb8aa3b, v58
	v_exp_f32_e32 v50, v50
	v_exp_f32_e32 v51, v51
	v_and_b32_e32 v60, 0xffff0000, v53
	v_lshlrev_b32_e32 v57, 16, v49
	v_lshlrev_b32_e32 v56, 16, v48
	v_pk_add_f32 v[50:51], v[50:51], 1.0 op_sel_hi:[1,0]
	v_and_b32_e32 v49, 0xffff0000, v49
	v_div_scale_f32 v53, s[2:3], v51, v51, v58
	v_rcp_f32_e32 v62, v53
	v_and_b32_e32 v48, 0xffff0000, v48
	v_fma_f32 v63, -v53, v62, 1.0
	v_fmac_f32_e32 v62, v63, v62
	v_div_scale_f32 v63, vcc, v58, v51, v58
	v_mul_f32_e32 v64, v63, v62
	v_fma_f32 v65, -v53, v64, v63
	v_fmac_f32_e32 v64, v65, v62
	v_fma_f32 v53, -v53, v64, v63
	v_div_fmas_f32 v53, v53, v62, v64
	v_div_fixup_f32 v51, v53, v51, v58
	v_div_scale_f32 v53, s[2:3], v50, v50, v59
	v_rcp_f32_e32 v58, v53
	s_nop 0
	v_fma_f32 v62, -v53, v58, 1.0
	v_fmac_f32_e32 v58, v62, v58
	v_div_scale_f32 v62, vcc, v59, v50, v59
	v_mul_f32_e32 v63, v62, v58
	v_fma_f32 v64, -v53, v63, v62
	v_fmac_f32_e32 v63, v64, v58
; __device__ __forceinline__ unsigned pk2(float lo, float hi) { return f2bf(lo) | (f2bf(hi) << 16); }
; __device__ __forceinline__ float silu(float x) { return x / (1.f + __expf(-x)); }
; __global__ void __launch_bounds__(NWAVES * 64, 2) hybrid_fwd(Args args) {
;     ...
;             for (int j = 0; j < 4; ++j) { float d[8]; float ss = 0.f;
; #pragma unroll
;                 for (int e = 0; e < 4; ++e) { const float d0 = bflo(a[j][e]) - lam * bflo(b[j][e]), d1 = bfhi(a[j][e]) - lam * bfhi(b[j][e]); d[2 * e] = d0; d[2 * e + 1] = d1; ss += d0 * d0 + d1 * d1; }
;                 ss += __shfl_xor(ss, 1); ss += __shfl_xor(ss, 2); ss += __shfl_xor(ss, 4); ss += __shfl_xor(ss, 8); ss += __shfl_xor(ss, 16);
;                 const float rstd = (1.f - LAMBDA_INIT) / sqrtf(ss * (1.f / 256.f) + RMS_EPS); v4u o;
; #pragma unroll
;                 for (int e = 0; e < 4; ++e) { const f32x4 s4 = (e >> 1) ? sl1 : sl0;
;                     o[e] = pk2(d[2 * e] * rstd * s4[(e & 1) * 2] * silu(bflo(gt[j][e])), d[2 * e + 1] * rstd * s4[(e & 1) * 2 + 1] * silu(bfhi(gt[j][e]))); }
;                 po[64 * j] = o;
;                 v4u o2;
; #pragma unroll
;                 for (int e = 0; e < 4; ++e) o2[e] = pk2(bflo(ab[j][e]) * silu(bflo(gm[j][e])), bfhi(ab[j][e]) * silu(bfhi(gm[j][e])));
;                 po[256 + 64 * j] = o2; }
	v_fma_f32 v53, -v53, v63, v62
	v_div_fmas_f32 v53, v53, v58, v63
	v_div_fixup_f32 v50, v53, v50, v59
	v_mul_f32_e32 v53, 0xbfb8aa3b, v60
	v_exp_f32_e32 v53, v53
	v_pk_mul_f32 v[50:51], v[50:51], v[56:57]
	v_pk_add_f32 v[52:53], v[52:53], 1.0 op_sel_hi:[1,0]
	s_nop 0
	v_div_scale_f32 v56, s[2:3], v53, v53, v60
	v_rcp_f32_e32 v57, v56
	s_nop 0
	v_fma_f32 v58, -v56, v57, 1.0
	v_fmac_f32_e32 v57, v58, v57
	v_div_scale_f32 v58, vcc, v60, v53, v60
	v_mul_f32_e32 v59, v58, v57
	v_fma_f32 v62, -v56, v59, v58
	v_fmac_f32_e32 v59, v62, v57
	v_fma_f32 v56, -v56, v59, v58
	v_div_fmas_f32 v56, v56, v57, v59
	v_div_fixup_f32 v53, v56, v53, v60
	v_div_scale_f32 v56, s[2:3], v52, v52, v61
	v_rcp_f32_e32 v57, v56
	s_nop 0
	v_fma_f32 v58, -v56, v57, 1.0
	v_fmac_f32_e32 v57, v58, v57
	v_div_scale_f32 v58, vcc, v61, v52, v61
	v_mul_f32_e32 v59, v58, v57
	v_fma_f32 v60, -v56, v59, v58
	v_fmac_f32_e32 v59, v60, v57
	v_fma_f32 v56, -v56, v59, v58
	v_div_fmas_f32 v56, v56, v57, v59
	v_div_fixup_f32 v52, v56, v52, v61
	v_pk_mul_f32 v[48:49], v[52:53], v[48:49]
	v_bfe_u32 v56, v47, 16, 1
	v_bfe_u32 v52, v49, 16, 1
	v_bfe_u32 v53, v48, 16, 1
	v_bfe_u32 v57, v46, 16, 1
	v_add3_u32 v46, v46, v57, s24
	v_add3_u32 v47, v47, v56, s24
	v_add3_u32 v48, v48, v53, s24
	v_add3_u32 v49, v49, v52, s24
	v_bfe_u32 v52, v54, 16, 1
	v_bfe_u32 v53, v55, 16, 1
	v_bfe_u32 v56, v50, 16, 1
	v_bfe_u32 v57, v51, 16, 1
	v_add3_u32 v51, v51, v57, s24
	v_add3_u32 v50, v50, v56, s24
	v_add3_u32 v53, v55, v53, s24
	v_add3_u32 v52, v54, v52, s24
	v_lshrrev_b32_e32 v52, 16, v52
	v_lshrrev_b32_e32 v53, 16, v53
	v_lshrrev_b32_e32 v50, 16, v50
	v_lshrrev_b32_e32 v51, 16, v51
	v_and_or_b32 v49, v49, s21, v51
	v_and_or_b32 v48, v48, s21, v50
	v_and_or_b32 v47, v47, s21, v53
	v_and_or_b32 v46, v46, s21, v52
	s_waitcnt vmcnt(10)
	v_and_b32_e32 v56, 0xffff0000, v34
	global_store_dwordx4 v[78:79], v[46:49], off offset:1024
	v_lshlrev_b32_e32 v50, 16, v42
	v_lshlrev_b32_e32 v51, 16, v43
	v_and_b32_e32 v48, 0xffff0000, v42
	v_and_b32_e32 v49, 0xffff0000, v43
	v_lshlrev_b32_e32 v46, 16, v44
	v_and_b32_e32 v42, 0xffff0000, v44
	v_lshlrev_b32_e32 v47, 16, v45
	v_and_b32_e32 v43, 0xffff0000, v45
	v_lshlrev_b32_e32 v45, 16, v39
	v_lshlrev_b32_e32 v44, 16, v38
	v_lshlrev_b32_e32 v53, 16, v35
	v_lshlrev_b32_e32 v54, 16, v34
	v_mul_f32_e32 v34, 0xbfb8aa3b, v56
	v_pk_fma_f32 v[44:45], v[2:3], v[50:51], v[44:45] neg_lo:[1,0,0] neg_hi:[1,0,0]
	v_mul_f32_e32 v50, 0xbfb8aa3b, v54
	v_exp_f32_e32 v52, v34
	v_mul_f32_e32 v34, 0xbfb8aa3b, v53
	v_exp_f32_e32 v50, v50
	v_exp_f32_e32 v51, v34
	v_and_b32_e32 v55, 0xffff0000, v35
	v_and_b32_e32 v39, 0xffff0000, v39
	v_and_b32_e32 v38, 0xffff0000, v38
	v_pk_add_f32 v[34:35], v[50:51], 1.0 op_sel_hi:[1,0]
	v_pk_fma_f32 v[38:39], v[2:3], v[48:49], v[38:39] neg_lo:[1,0,0] neg_hi:[1,0,0]
	v_div_scale_f32 v50, s[2:3], v35, v35, v53
	v_rcp_f32_e32 v51, v50
	v_pk_mul_f32 v[48:49], v[38:39], v[38:39]
	v_fma_f32 v57, -v50, v51, 1.0
	v_fmac_f32_e32 v51, v57, v51
	v_div_scale_f32 v57, vcc, v53, v35, v53
	v_mul_f32_e32 v58, v57, v51
	v_fma_f32 v59, -v50, v58, v57
	v_fmac_f32_e32 v58, v59, v51
	v_fma_f32 v50, -v50, v58, v57
	v_div_fmas_f32 v50, v50, v51, v58
	v_div_fixup_f32 v35, v50, v35, v53
	v_div_scale_f32 v50, s[2:3], v34, v34, v54
	v_rcp_f32_e32 v51, v50
	v_pk_fma_f32 v[48:49], v[44:45], v[44:45], v[48:49]
	v_fma_f32 v53, -v50, v51, 1.0
	v_fmac_f32_e32 v51, v53, v51
	v_div_scale_f32 v53, vcc, v54, v34, v54
	v_mul_f32_e32 v57, v53, v51
	v_fma_f32 v58, -v50, v57, v53
	v_fmac_f32_e32 v57, v58, v51
	v_fma_f32 v50, -v50, v57, v53
	v_div_fmas_f32 v50, v50, v51, v57
	v_div_fixup_f32 v34, v50, v34, v54
	v_mul_f32_e32 v50, 0xbfb8aa3b, v55
	v_exp_f32_e32 v53, v50
	v_add_f32_e32 v48, v48, v49
	v_pk_add_f32 v[50:51], v[52:53], 1.0 op_sel_hi:[1,0]
	s_nop 0
	v_div_scale_f32 v52, s[2:3], v51, v51, v55
	v_rcp_f32_e32 v53, v52
	s_nop 0
	v_fma_f32 v54, -v52, v53, 1.0
	v_fmac_f32_e32 v53, v54, v53
	v_div_scale_f32 v54, vcc, v55, v51, v55
	v_mul_f32_e32 v57, v54, v53
	v_fma_f32 v58, -v52, v57, v54
	v_fmac_f32_e32 v57, v58, v53
	v_fma_f32 v52, -v52, v57, v54
	v_div_fmas_f32 v52, v52, v53, v57
	v_div_fixup_f32 v51, v52, v51, v55
	v_div_scale_f32 v52, s[2:3], v50, v50, v56
	v_rcp_f32_e32 v53, v52
	s_nop 0
	v_fma_f32 v54, -v52, v53, 1.0
	v_fmac_f32_e32 v53, v54, v53
	v_div_scale_f32 v54, vcc, v56, v50, v56
	v_mul_f32_e32 v55, v54, v53
	v_fma_f32 v57, -v52, v55, v54
	v_fmac_f32_e32 v55, v57, v53
	v_fma_f32 v52, -v52, v55, v54
	v_div_fmas_f32 v52, v52, v53, v55
	v_div_fixup_f32 v50, v52, v50, v56
	v_lshlrev_b32_e32 v53, 16, v41
	v_lshlrev_b32_e32 v52, 16, v40
	v_and_b32_e32 v41, 0xffff0000, v41
	v_and_b32_e32 v40, 0xffff0000, v40
	v_pk_fma_f32 v[40:41], v[2:3], v[42:43], v[40:41] neg_lo:[1,0,0] neg_hi:[1,0,0]
	v_pk_fma_f32 v[46:47], v[2:3], v[46:47], v[52:53] neg_lo:[1,0,0] neg_hi:[1,0,0]
	v_pk_mul_f32 v[42:43], v[40:41], v[40:41]
	s_nop 0
	v_pk_fma_f32 v[42:43], v[46:47], v[46:47], v[42:43]
	s_nop 0
	v_add_f32_e32 v42, v48, v42
	v_add_f32_e32 v42, v42, v43
	ds_bpermute_b32 v43, v88, v42
	s_waitcnt lgkmcnt(0)
	v_add_f32_e32 v42, v42, v43
	ds_bpermute_b32 v43, v89, v42
	s_waitcnt lgkmcnt(0)
	v_add_f32_e32 v42, v42, v43
	ds_bpermute_b32 v43, v90, v42
	s_waitcnt lgkmcnt(0)
	v_add_f32_e32 v42, v42, v43
	ds_bpermute_b32 v43, v91, v42
	s_waitcnt lgkmcnt(0)
	v_add_f32_e32 v42, v42, v43
	ds_bpermute_b32 v43, v92, v42
	s_waitcnt lgkmcnt(0)
; __device__ __forceinline__ unsigned pk2(float lo, float hi) { return f2bf(lo) | (f2bf(hi) << 16); }
; __device__ __forceinline__ float silu(float x) { return x / (1.f + __expf(-x)); }
; __global__ void __launch_bounds__(NWAVES * 64, 2) hybrid_fwd(Args args) {
;     ...
;             for (int j = 0; j < 4; ++j) { float d[8]; float ss = 0.f;
; #pragma unroll
;                 for (int e = 0; e < 4; ++e) { const float d0 = bflo(a[j][e]) - lam * bflo(b[j][e]), d1 = bfhi(a[j][e]) - lam * bfhi(b[j][e]); d[2 * e] = d0; d[2 * e + 1] = d1; ss += d0 * d0 + d1 * d1; }
;                 ss += __shfl_xor(ss, 1); ss += __shfl_xor(ss, 2); ss += __shfl_xor(ss, 4); ss += __shfl_xor(ss, 8); ss += __shfl_xor(ss, 16);
;                 const float rstd = (1.f - LAMBDA_INIT) / sqrtf(ss * (1.f / 256.f) + RMS_EPS); v4u o;
; #pragma unroll
;                 for (int e = 0; e < 4; ++e) { const f32x4 s4 = (e >> 1) ? sl1 : sl0;
;                     o[e] = pk2(d[2 * e] * rstd * s4[(e & 1) * 2] * silu(bflo(gt[j][e])), d[2 * e + 1] * rstd * s4[(e & 1) * 2 + 1] * silu(bfhi(gt[j][e]))); }
;                 po[64 * j] = o;
;                 v4u o2;
; #pragma unroll
;                 for (int e = 0; e < 4; ++e) o2[e] = pk2(bflo(ab[j][e]) * silu(bflo(gm[j][e])), bfhi(ab[j][e]) * silu(bfhi(gm[j][e])));
;                 po[256 + 64 * j] = o2; }
	v_add_f32_e32 v42, v42, v43
	v_fmamk_f32 v42, v42, 0x3b800000, v93
	v_cmp_gt_f32_e32 vcc, s22, v42
	v_mul_f32_e32 v43, 0x4f800000, v42
	s_nop 0
	v_cndmask_b32_e32 v42, v42, v43, vcc
	v_sqrt_f32_e32 v43, v42
	s_nop 0
	v_add_u32_e32 v48, -1, v43
	v_fma_f32 v49, -v48, v43, v42
	v_cmp_ge_f32_e64 s[2:3], 0, v49
	v_add_u32_e32 v49, 1, v43
	s_nop 0
	v_cndmask_b32_e64 v48, v43, v48, s[2:3]
	v_fma_f32 v43, -v49, v43, v42
	v_cmp_lt_f32_e64 s[2:3], 0, v43
	s_nop 1
	v_cndmask_b32_e64 v43, v48, v49, s[2:3]
	v_mul_f32_e32 v48, 0x37800000, v43
	v_cndmask_b32_e32 v43, v43, v48, vcc
	v_cmp_class_f32_e32 vcc, v42, v94
	s_nop 1
	v_cndmask_b32_e32 v42, v43, v42, vcc
	v_div_scale_f32 v43, s[2:3], v42, v42, s23
	v_rcp_f32_e32 v48, v43
	s_nop 0
	v_fma_f32 v49, -v43, v48, 1.0
	v_fmac_f32_e32 v48, v49, v48
	v_div_scale_f32 v49, vcc, s23, v42, s23
	v_mul_f32_e32 v52, v49, v48
	v_fma_f32 v53, -v43, v52, v49
	v_fmac_f32_e32 v52, v53, v48
	v_fma_f32 v43, -v43, v52, v49
	v_div_fmas_f32 v43, v43, v48, v52
	v_div_fixup_f32 v42, v43, v42, s23
	v_pk_mul_f32 v[44:45], v[42:43], v[44:45] op_sel_hi:[0,1]
	v_pk_mul_f32 v[44:45], v[0:1], v[44:45]
	v_pk_mul_f32 v[38:39], v[42:43], v[38:39] op_sel_hi:[0,1]
	v_lshlrev_b32_e32 v43, 16, v37
	v_lshlrev_b32_e32 v48, 16, v36
	v_pk_mul_f32 v[34:35], v[44:45], v[34:35]
	v_mul_f32_e32 v44, 0xbfb8aa3b, v48
	v_and_b32_e32 v49, 0xffff0000, v37
	v_mul_f32_e32 v37, 0xbfb8aa3b, v43
	v_exp_f32_e32 v44, v44
	v_exp_f32_e32 v45, v37
	v_pk_mul_f32 v[38:39], v[82:83], v[38:39]
	v_pk_mul_f32 v[46:47], v[42:43], v[46:47] op_sel_hi:[0,1]
	v_pk_mul_f32 v[38:39], v[38:39], v[50:51]
	v_pk_add_f32 v[44:45], v[44:45], 1.0 op_sel_hi:[1,0]
	v_and_b32_e32 v50, 0xffff0000, v36
	v_div_scale_f32 v37, s[2:3], v45, v45, v43
	v_rcp_f32_e32 v51, v37
	v_mul_f32_e32 v36, 0xbfb8aa3b, v50
	v_exp_f32_e32 v36, v36
	v_pk_mul_f32 v[46:47], v[4:5], v[46:47]
	v_fma_f32 v52, -v37, v51, 1.0
	v_fmac_f32_e32 v51, v52, v51
	v_div_scale_f32 v52, vcc, v43, v45, v43
	v_mul_f32_e32 v53, v52, v51
	v_fma_f32 v54, -v37, v53, v52
	v_fmac_f32_e32 v53, v54, v51
	v_fma_f32 v37, -v37, v53, v52
	v_div_fmas_f32 v37, v37, v51, v53
	v_div_fixup_f32 v45, v37, v45, v43
	v_div_scale_f32 v37, s[2:3], v44, v44, v48
	v_rcp_f32_e32 v43, v37
	s_nop 0
	v_fma_f32 v51, -v37, v43, 1.0
	v_fmac_f32_e32 v43, v51, v43
	v_div_scale_f32 v51, vcc, v48, v44, v48
	v_mul_f32_e32 v52, v51, v43
	v_fma_f32 v53, -v37, v52, v51
	v_fmac_f32_e32 v52, v53, v43
	v_fma_f32 v37, -v37, v52, v51
	v_div_fmas_f32 v37, v37, v43, v52
	v_div_fixup_f32 v44, v37, v44, v48
	v_mul_f32_e32 v37, 0xbfb8aa3b, v49
	v_exp_f32_e32 v37, v37
	v_pk_mul_f32 v[40:41], v[42:43], v[40:41] op_sel_hi:[0,1]
	v_pk_mul_f32 v[44:45], v[46:47], v[44:45]
	v_pk_mul_f32 v[40:41], v[84:85], v[40:41]
	v_pk_add_f32 v[36:37], v[36:37], 1.0 op_sel_hi:[1,0]
	s_nop 0
	v_div_scale_f32 v42, s[2:3], v37, v37, v49
	v_rcp_f32_e32 v43, v42
	s_nop 0
	v_fma_f32 v46, -v42, v43, 1.0
	v_fmac_f32_e32 v43, v46, v43
	v_div_scale_f32 v46, vcc, v49, v37, v49
	v_mul_f32_e32 v47, v46, v43
	v_fma_f32 v48, -v42, v47, v46
	v_fmac_f32_e32 v47, v48, v43
	v_fma_f32 v42, -v42, v47, v46
	v_div_fmas_f32 v42, v42, v43, v47
	v_div_fixup_f32 v37, v42, v37, v49
	v_div_scale_f32 v42, s[2:3], v36, v36, v50
	v_rcp_f32_e32 v43, v42
	s_nop 0
	v_fma_f32 v46, -v42, v43, 1.0
	v_fmac_f32_e32 v43, v46, v43
	v_div_scale_f32 v46, vcc, v50, v36, v50
	v_mul_f32_e32 v47, v46, v43
	v_fma_f32 v48, -v42, v47, v46
	v_fmac_f32_e32 v47, v48, v43
	v_fma_f32 v42, -v42, v47, v46
	v_div_fmas_f32 v42, v42, v43, v47
	v_div_fixup_f32 v36, v42, v36, v50
	v_pk_mul_f32 v[36:37], v[40:41], v[36:37]
	v_bfe_u32 v42, v39, 16, 1
	v_bfe_u32 v40, v37, 16, 1
	v_bfe_u32 v41, v36, 16, 1
	v_bfe_u32 v43, v38, 16, 1
	v_add3_u32 v38, v38, v43, s24
	v_add3_u32 v39, v39, v42, s24
	v_add3_u32 v36, v36, v41, s24
	v_add3_u32 v37, v37, v40, s24
	v_bfe_u32 v40, v34, 16, 1
	v_bfe_u32 v41, v35, 16, 1
	v_bfe_u32 v42, v44, 16, 1
	v_bfe_u32 v43, v45, 16, 1
	v_add3_u32 v43, v45, v43, s24
	v_add3_u32 v42, v44, v42, s24
	v_add3_u32 v35, v35, v41, s24
	v_add3_u32 v34, v34, v40, s24
	v_lshrrev_b32_e32 v34, 16, v34
	v_lshrrev_b32_e32 v35, 16, v35
	v_lshrrev_b32_e32 v40, 16, v42
	v_lshrrev_b32_e32 v41, 16, v43
	v_and_or_b32 v37, v37, s21, v41
	v_and_or_b32 v36, v36, s21, v40
	v_and_or_b32 v35, v39, s21, v35
	v_and_or_b32 v34, v38, s21, v34
	s_waitcnt vmcnt(9)
; __device__ __forceinline__ unsigned pk2(float lo, float hi) { return f2bf(lo) | (f2bf(hi) << 16); }
; __device__ __forceinline__ float silu(float x) { return x / (1.f + __expf(-x)); }
; __global__ void __launch_bounds__(NWAVES * 64, 2) hybrid_fwd(Args args) {
;     ...
;             for (int j = 0; j < 4; ++j) { float d[8]; float ss = 0.f;
; #pragma unroll
;                 for (int e = 0; e < 4; ++e) { const float d0 = bflo(a[j][e]) - lam * bflo(b[j][e]), d1 = bfhi(a[j][e]) - lam * bfhi(b[j][e]); d[2 * e] = d0; d[2 * e + 1] = d1; ss += d0 * d0 + d1 * d1; }
;                 ss += __shfl_xor(ss, 1); ss += __shfl_xor(ss, 2); ss += __shfl_xor(ss, 4); ss += __shfl_xor(ss, 8); ss += __shfl_xor(ss, 16);
;                 const float rstd = (1.f - LAMBDA_INIT) / sqrtf(ss * (1.f / 256.f) + RMS_EPS); v4u o;
; #pragma unroll
;                 for (int e = 0; e < 4; ++e) { const f32x4 s4 = (e >> 1) ? sl1 : sl0;
;                     o[e] = pk2(d[2 * e] * rstd * s4[(e & 1) * 2] * silu(bflo(gt[j][e])), d[2 * e + 1] * rstd * s4[(e & 1) * 2 + 1] * silu(bfhi(gt[j][e]))); }
;                 po[64 * j] = o;
;                 v4u o2;
; #pragma unroll
;                 for (int e = 0; e < 4; ++e) o2[e] = pk2(bflo(ab[j][e]) * silu(bflo(gm[j][e])), bfhi(ab[j][e]) * silu(bfhi(gm[j][e])));
;                 po[256 + 64 * j] = o2; }
	v_lshlrev_b32_e32 v38, 16, v31
	v_lshlrev_b32_e32 v39, 16, v30
	global_store_dwordx4 v[80:81], v[34:37], off offset:2048
	v_and_b32_e32 v40, 0xffff0000, v31
	v_mul_f32_e32 v31, 0xbfb8aa3b, v38
	v_mul_f32_e32 v34, 0xbfb8aa3b, v39
	v_exp_f32_e32 v34, v34
	v_exp_f32_e32 v35, v31
	v_and_b32_e32 v41, 0xffff0000, v30
	v_mul_f32_e32 v30, 0xbfb8aa3b, v41
	v_exp_f32_e32 v30, v30
	v_pk_add_f32 v[34:35], v[34:35], 1.0 op_sel_hi:[1,0]
	v_lshlrev_b32_e32 v37, 16, v27
	v_div_scale_f32 v31, s[2:3], v35, v35, v38
	v_rcp_f32_e32 v42, v31
	v_lshlrev_b32_e32 v36, 16, v26
	v_and_b32_e32 v27, 0xffff0000, v27
	v_and_b32_e32 v26, 0xffff0000, v26
	v_fma_f32 v43, -v31, v42, 1.0
	v_fmac_f32_e32 v42, v43, v42
	v_div_scale_f32 v43, vcc, v38, v35, v38
	v_mul_f32_e32 v44, v43, v42
	v_fma_f32 v45, -v31, v44, v43
	v_fmac_f32_e32 v44, v45, v42
	v_fma_f32 v31, -v31, v44, v43
	v_div_fmas_f32 v31, v31, v42, v44
	v_div_fixup_f32 v35, v31, v35, v38
	v_div_scale_f32 v31, s[2:3], v34, v34, v39
	v_rcp_f32_e32 v38, v31
	s_nop 0
	v_fma_f32 v42, -v31, v38, 1.0
	v_fmac_f32_e32 v38, v42, v38
	v_div_scale_f32 v42, vcc, v39, v34, v39
	v_mul_f32_e32 v43, v42, v38
	v_fma_f32 v44, -v31, v43, v42
	v_fmac_f32_e32 v43, v44, v38
	v_fma_f32 v31, -v31, v43, v42
	v_div_fmas_f32 v31, v31, v38, v43
	v_div_fixup_f32 v34, v31, v34, v39
	v_mul_f32_e32 v31, 0xbfb8aa3b, v40
	v_exp_f32_e32 v31, v31
	v_pk_mul_f32 v[34:35], v[34:35], v[36:37]
	v_pk_add_f32 v[30:31], v[30:31], 1.0 op_sel_hi:[1,0]
	s_nop 0
	v_div_scale_f32 v36, s[2:3], v31, v31, v40
	v_rcp_f32_e32 v37, v36
	s_nop 0
	v_fma_f32 v38, -v36, v37, 1.0
	v_fmac_f32_e32 v37, v38, v37
	v_div_scale_f32 v38, vcc, v40, v31, v40
	v_mul_f32_e32 v39, v38, v37
	v_fma_f32 v42, -v36, v39, v38
	v_fmac_f32_e32 v39, v42, v37
	v_fma_f32 v36, -v36, v39, v38
	v_div_fmas_f32 v36, v36, v37, v39
	v_div_fixup_f32 v31, v36, v31, v40
	v_div_scale_f32 v36, s[2:3], v30, v30, v41
	v_rcp_f32_e32 v37, v36
	s_nop 0
	v_fma_f32 v38, -v36, v37, 1.0
	v_fmac_f32_e32 v37, v38, v37
	v_div_scale_f32 v38, vcc, v41, v30, v41
	v_mul_f32_e32 v39, v38, v37
	v_fma_f32 v40, -v36, v39, v38
	v_fmac_f32_e32 v39, v40, v37
	v_fma_f32 v36, -v36, v39, v38
	v_div_fmas_f32 v36, v36, v37, v39
	v_div_fixup_f32 v30, v36, v30, v41
	v_and_b32_e32 v41, 0xffff0000, v32
	v_pk_mul_f32 v[26:27], v[30:31], v[26:27]
	v_lshlrev_b32_e32 v38, 16, v33
	v_lshlrev_b32_e32 v39, 16, v32
	v_mul_f32_e32 v31, 0xbfb8aa3b, v41
	v_mul_f32_e32 v30, 0xbfb8aa3b, v39
	v_exp_f32_e32 v32, v31
	v_mul_f32_e32 v31, 0xbfb8aa3b, v38
	v_exp_f32_e32 v30, v30
	v_exp_f32_e32 v31, v31
	v_and_b32_e32 v40, 0xffff0000, v33
	v_lshlrev_b32_e32 v37, 16, v29
	v_lshlrev_b32_e32 v36, 16, v28
	v_pk_add_f32 v[30:31], v[30:31], 1.0 op_sel_hi:[1,0]
	v_and_b32_e32 v29, 0xffff0000, v29
	v_div_scale_f32 v33, s[2:3], v31, v31, v38
	v_rcp_f32_e32 v42, v33
	v_and_b32_e32 v28, 0xffff0000, v28
	v_fma_f32 v43, -v33, v42, 1.0
	v_fmac_f32_e32 v42, v43, v42
	v_div_scale_f32 v43, vcc, v38, v31, v38
	v_mul_f32_e32 v44, v43, v42
	v_fma_f32 v45, -v33, v44, v43
	v_fmac_f32_e32 v44, v45, v42
	v_fma_f32 v33, -v33, v44, v43
	v_div_fmas_f32 v33, v33, v42, v44
	v_div_fixup_f32 v31, v33, v31, v38
	v_div_scale_f32 v33, s[2:3], v30, v30, v39
	v_rcp_f32_e32 v38, v33
	s_nop 0
	v_fma_f32 v42, -v33, v38, 1.0
	v_fmac_f32_e32 v38, v42, v38
	v_div_scale_f32 v42, vcc, v39, v30, v39
	v_mul_f32_e32 v43, v42, v38
	v_fma_f32 v44, -v33, v43, v42
	v_fmac_f32_e32 v43, v44, v38
	v_fma_f32 v33, -v33, v43, v42
	v_div_fmas_f32 v33, v33, v38, v43
	v_div_fixup_f32 v30, v33, v30, v39
	v_mul_f32_e32 v33, 0xbfb8aa3b, v40
	v_exp_f32_e32 v33, v33
	v_pk_mul_f32 v[30:31], v[30:31], v[36:37]
	v_pk_add_f32 v[32:33], v[32:33], 1.0 op_sel_hi:[1,0]
	s_nop 0
	v_div_scale_f32 v36, s[2:3], v33, v33, v40
	v_rcp_f32_e32 v37, v36
	s_nop 0
	v_fma_f32 v38, -v36, v37, 1.0
	v_fmac_f32_e32 v37, v38, v37
	v_div_scale_f32 v38, vcc, v40, v33, v40
	v_mul_f32_e32 v39, v38, v37
	v_fma_f32 v42, -v36, v39, v38
	v_fmac_f32_e32 v39, v42, v37
	v_fma_f32 v36, -v36, v39, v38
	v_div_fmas_f32 v36, v36, v37, v39
	v_div_fixup_f32 v33, v36, v33, v40
	v_div_scale_f32 v36, s[2:3], v32, v32, v41
	v_rcp_f32_e32 v37, v36
	s_nop 0
	v_fma_f32 v38, -v36, v37, 1.0
	v_fmac_f32_e32 v37, v38, v37
	v_div_scale_f32 v38, vcc, v41, v32, v41
	v_mul_f32_e32 v39, v38, v37
	v_fma_f32 v40, -v36, v39, v38
	v_fmac_f32_e32 v39, v40, v37
	v_fma_f32 v36, -v36, v39, v38
	v_div_fmas_f32 v36, v36, v37, v39
	v_div_fixup_f32 v32, v36, v32, v41
	v_pk_mul_f32 v[28:29], v[32:33], v[28:29]
	v_bfe_u32 v36, v27, 16, 1
	v_bfe_u32 v32, v29, 16, 1
	v_bfe_u32 v33, v28, 16, 1
	v_bfe_u32 v37, v26, 16, 1
	v_add3_u32 v26, v26, v37, s24
	v_add3_u32 v27, v27, v36, s24
	v_add3_u32 v28, v28, v33, s24
	v_add3_u32 v29, v29, v32, s24
	v_bfe_u32 v32, v34, 16, 1
	v_bfe_u32 v33, v35, 16, 1
	v_bfe_u32 v36, v30, 16, 1
	v_bfe_u32 v37, v31, 16, 1
	v_add3_u32 v31, v31, v37, s24
	v_add3_u32 v30, v30, v36, s24
	v_add3_u32 v33, v35, v33, s24
	v_add3_u32 v32, v34, v32, s24
	v_lshrrev_b32_e32 v32, 16, v32
	v_lshrrev_b32_e32 v33, 16, v33
	v_lshrrev_b32_e32 v30, 16, v30
	v_lshrrev_b32_e32 v31, 16, v31
	v_and_or_b32 v29, v29, s21, v31
	v_and_or_b32 v28, v28, s21, v30
	v_and_or_b32 v27, v27, s21, v33
	v_and_or_b32 v26, v26, s21, v32
	global_store_dwordx4 v[78:79], v[26:29], off offset:2048
	s_waitcnt vmcnt(9)
	v_lshlrev_b32_e32 v30, 16, v22
	v_lshlrev_b32_e32 v31, 16, v23
	v_and_b32_e32 v28, 0xffff0000, v22
	v_and_b32_e32 v29, 0xffff0000, v23
	v_lshlrev_b32_e32 v26, 16, v24
	v_and_b32_e32 v22, 0xffff0000, v24
	v_lshlrev_b32_e32 v27, 16, v25
	v_and_b32_e32 v23, 0xffff0000, v25
	v_lshlrev_b32_e32 v25, 16, v19
	v_lshlrev_b32_e32 v24, 16, v18
	v_and_b32_e32 v19, 0xffff0000, v19
	v_and_b32_e32 v18, 0xffff0000, v18
	v_pk_fma_f32 v[28:29], v[2:3], v[28:29], v[18:19] neg_lo:[1,0,0] neg_hi:[1,0,0]
	v_pk_fma_f32 v[30:31], v[2:3], v[30:31], v[24:25] neg_lo:[1,0,0] neg_hi:[1,0,0]
	v_pk_mul_f32 v[18:19], v[28:29], v[28:29]
	s_waitcnt vmcnt(8)
; __device__ __forceinline__ unsigned pk2(float lo, float hi) { return f2bf(lo) | (f2bf(hi) << 16); }
; __device__ __forceinline__ float silu(float x) { return x / (1.f + __expf(-x)); }
; __global__ void __launch_bounds__(NWAVES * 64, 2) hybrid_fwd(Args args) {
;     ...
;             for (int j = 0; j < 4; ++j) { float d[8]; float ss = 0.f;
; #pragma unroll
;                 for (int e = 0; e < 4; ++e) { const float d0 = bflo(a[j][e]) - lam * bflo(b[j][e]), d1 = bfhi(a[j][e]) - lam * bfhi(b[j][e]); d[2 * e] = d0; d[2 * e + 1] = d1; ss += d0 * d0 + d1 * d1; }
;                 ss += __shfl_xor(ss, 1); ss += __shfl_xor(ss, 2); ss += __shfl_xor(ss, 4); ss += __shfl_xor(ss, 8); ss += __shfl_xor(ss, 16);
;                 const float rstd = (1.f - LAMBDA_INIT) / sqrtf(ss * (1.f / 256.f) + RMS_EPS); v4u o;
; #pragma unroll
;                 for (int e = 0; e < 4; ++e) { const f32x4 s4 = (e >> 1) ? sl1 : sl0;
;                     o[e] = pk2(d[2 * e] * rstd * s4[(e & 1) * 2] * silu(bflo(gt[j][e])), d[2 * e + 1] * rstd * s4[(e & 1) * 2 + 1] * silu(bfhi(gt[j][e]))); }
;                 po[64 * j] = o;
;                 v4u o2;
; #pragma unroll
;                 for (int e = 0; e < 4; ++e) o2[e] = pk2(bflo(ab[j][e]) * silu(bflo(gm[j][e])), bfhi(ab[j][e]) * silu(bfhi(gm[j][e])));
;                 po[256 + 64 * j] = o2; }
	v_lshlrev_b32_e32 v24, 16, v15
	v_lshlrev_b32_e32 v25, 16, v14
	v_pk_fma_f32 v[32:33], v[30:31], v[30:31], v[18:19]
	v_mul_f32_e32 v18, 0xbfb8aa3b, v25
	v_and_b32_e32 v34, 0xffff0000, v15
	v_mul_f32_e32 v15, 0xbfb8aa3b, v24
	v_exp_f32_e32 v18, v18
	v_exp_f32_e32 v19, v15
	v_and_b32_e32 v36, 0xffff0000, v14
	v_mul_f32_e32 v14, 0xbfb8aa3b, v36
	v_exp_f32_e32 v14, v14
	v_pk_add_f32 v[18:19], v[18:19], 1.0 op_sel_hi:[1,0]
	s_nop 0
	v_div_scale_f32 v15, s[2:3], v19, v19, v24
	v_rcp_f32_e32 v35, v15
	s_nop 0
	v_fma_f32 v37, -v15, v35, 1.0
	v_fmac_f32_e32 v35, v37, v35
	v_div_scale_f32 v37, vcc, v24, v19, v24
	v_mul_f32_e32 v38, v37, v35
	v_fma_f32 v39, -v15, v38, v37
	v_fmac_f32_e32 v38, v39, v35
	v_fma_f32 v15, -v15, v38, v37
	v_div_fmas_f32 v15, v15, v35, v38
	v_div_fixup_f32 v19, v15, v19, v24
	v_div_scale_f32 v15, s[2:3], v18, v18, v25
	v_rcp_f32_e32 v24, v15
	s_nop 0
	v_fma_f32 v35, -v15, v24, 1.0
	v_fmac_f32_e32 v24, v35, v24
	v_div_scale_f32 v35, vcc, v25, v18, v25
	v_mul_f32_e32 v37, v35, v24
	v_fma_f32 v38, -v15, v37, v35
	v_fmac_f32_e32 v37, v38, v24
	v_fma_f32 v15, -v15, v37, v35
	v_div_fmas_f32 v15, v15, v24, v37
	v_div_fixup_f32 v18, v15, v18, v25
	v_mul_f32_e32 v15, 0xbfb8aa3b, v34
	v_exp_f32_e32 v15, v15
	s_nop 0
	v_pk_add_f32 v[14:15], v[14:15], 1.0 op_sel_hi:[1,0]
	s_nop 0
	v_div_scale_f32 v24, s[2:3], v15, v15, v34
	v_rcp_f32_e32 v25, v24
	s_nop 0
	v_fma_f32 v35, -v24, v25, 1.0
	v_fmac_f32_e32 v25, v35, v25
	v_div_scale_f32 v35, vcc, v34, v15, v34
	v_mul_f32_e32 v37, v35, v25
	v_fma_f32 v38, -v24, v37, v35
	v_fmac_f32_e32 v37, v38, v25
	v_fma_f32 v24, -v24, v37, v35
	v_div_fmas_f32 v24, v24, v25, v37
	v_div_fixup_f32 v35, v24, v15, v34
	v_div_scale_f32 v15, s[2:3], v14, v14, v36
	v_rcp_f32_e32 v24, v15
	s_nop 0
	v_fma_f32 v25, -v15, v24, 1.0
	v_fmac_f32_e32 v24, v25, v24
	v_div_scale_f32 v25, vcc, v36, v14, v36
	v_mul_f32_e32 v34, v25, v24
	v_fma_f32 v37, -v15, v34, v25
	v_fmac_f32_e32 v34, v37, v24
	v_fma_f32 v15, -v15, v34, v25
	v_div_fmas_f32 v15, v15, v24, v34
	v_div_fixup_f32 v34, v15, v14, v36
	v_lshlrev_b32_e32 v15, 16, v21
	v_lshlrev_b32_e32 v14, 16, v20
	v_pk_fma_f32 v[24:25], v[2:3], v[26:27], v[14:15] neg_lo:[1,0,0] neg_hi:[1,0,0]
	v_and_b32_e32 v15, 0xffff0000, v21
	v_and_b32_e32 v14, 0xffff0000, v20
	v_pk_fma_f32 v[14:15], v[2:3], v[22:23], v[14:15] neg_lo:[1,0,0] neg_hi:[1,0,0]
	v_add_f32_e32 v22, v32, v33
	v_pk_mul_f32 v[20:21], v[14:15], v[14:15]
	s_nop 0
	v_pk_fma_f32 v[20:21], v[24:25], v[24:25], v[20:21]
	s_nop 0
	v_add_f32_e32 v20, v22, v20
	v_add_f32_e32 v20, v20, v21
	ds_bpermute_b32 v21, v88, v20
	s_waitcnt lgkmcnt(0)
	v_add_f32_e32 v20, v20, v21
	ds_bpermute_b32 v21, v89, v20
	s_waitcnt lgkmcnt(0)
	v_add_f32_e32 v20, v20, v21
	ds_bpermute_b32 v21, v90, v20
	s_waitcnt lgkmcnt(0)
	v_add_f32_e32 v20, v20, v21
	ds_bpermute_b32 v21, v91, v20
	s_waitcnt lgkmcnt(0)
	v_add_f32_e32 v20, v20, v21
	ds_bpermute_b32 v21, v92, v20
	s_waitcnt lgkmcnt(0)
	v_add_f32_e32 v20, v20, v21
	v_fmamk_f32 v20, v20, 0x3b800000, v93
	v_cmp_gt_f32_e32 vcc, s22, v20
	v_mul_f32_e32 v21, 0x4f800000, v20
	s_nop 0
	v_cndmask_b32_e32 v20, v20, v21, vcc
	v_sqrt_f32_e32 v21, v20
	s_nop 0
	v_add_u32_e32 v22, -1, v21
	v_fma_f32 v23, -v22, v21, v20
	v_cmp_ge_f32_e64 s[2:3], 0, v23
	v_add_u32_e32 v23, 1, v21
	s_nop 0
	v_cndmask_b32_e64 v22, v21, v22, s[2:3]
	v_fma_f32 v21, -v23, v21, v20
	v_cmp_lt_f32_e64 s[2:3], 0, v21
	s_nop 1
	v_cndmask_b32_e64 v21, v22, v23, s[2:3]
	v_mul_f32_e32 v22, 0x37800000, v21
	v_cndmask_b32_e32 v21, v21, v22, vcc
	v_cmp_class_f32_e32 vcc, v20, v94
	s_nop 1
	v_cndmask_b32_e32 v20, v21, v20, vcc
	v_div_scale_f32 v21, s[2:3], v20, v20, s23
	v_rcp_f32_e32 v22, v21
	s_nop 0
	v_fma_f32 v23, -v21, v22, 1.0
	v_fmac_f32_e32 v22, v23, v22
	v_div_scale_f32 v23, vcc, s23, v20, s23
	v_mul_f32_e32 v26, v23, v22
	v_fma_f32 v27, -v21, v26, v23
	v_fmac_f32_e32 v26, v27, v22
	v_fma_f32 v21, -v21, v26, v23
	v_div_fmas_f32 v21, v21, v22, v26
	v_div_fixup_f32 v22, v21, v20, s23
	v_pk_mul_f32 v[20:21], v[22:23], v[30:31] op_sel_hi:[0,1]
	v_pk_mul_f32 v[20:21], v[0:1], v[20:21]
	v_and_b32_e32 v30, 0xffff0000, v16
	v_pk_mul_f32 v[18:19], v[20:21], v[18:19]
	v_pk_mul_f32 v[20:21], v[22:23], v[28:29] op_sel_hi:[0,1]
	v_lshlrev_b32_e32 v23, 16, v17
	v_lshlrev_b32_e32 v28, 16, v16
	v_mul_f32_e32 v26, 0xbfb8aa3b, v28
	v_and_b32_e32 v29, 0xffff0000, v17
	v_mul_f32_e32 v17, 0xbfb8aa3b, v23
	v_exp_f32_e32 v26, v26
	v_exp_f32_e32 v27, v17
	v_pk_mul_f32 v[20:21], v[82:83], v[20:21]
	v_pk_mul_f32 v[24:25], v[22:23], v[24:25] op_sel_hi:[0,1]
	v_pk_mul_f32 v[20:21], v[20:21], v[34:35]
	v_pk_add_f32 v[26:27], v[26:27], 1.0 op_sel_hi:[1,0]
	v_mul_f32_e32 v16, 0xbfb8aa3b, v30
	v_div_scale_f32 v17, s[2:3], v27, v27, v23
	v_rcp_f32_e32 v31, v17
	v_exp_f32_e32 v16, v16
	v_pk_mul_f32 v[24:25], v[4:5], v[24:25]
	v_fma_f32 v32, -v17, v31, 1.0
	v_fmac_f32_e32 v31, v32, v31
	v_div_scale_f32 v32, vcc, v23, v27, v23
	v_mul_f32_e32 v33, v32, v31
	v_fma_f32 v34, -v17, v33, v32
	v_fmac_f32_e32 v33, v34, v31
	v_fma_f32 v17, -v17, v33, v32
	v_div_fmas_f32 v17, v17, v31, v33
	v_div_fixup_f32 v27, v17, v27, v23
	v_div_scale_f32 v17, s[2:3], v26, v26, v28
	v_rcp_f32_e32 v23, v17
	s_nop 0
	v_fma_f32 v31, -v17, v23, 1.0
	v_fmac_f32_e32 v23, v31, v23
	v_div_scale_f32 v31, vcc, v28, v26, v28
	v_mul_f32_e32 v32, v31, v23
	v_fma_f32 v33, -v17, v32, v31
	v_fmac_f32_e32 v32, v33, v23
	v_fma_f32 v17, -v17, v32, v31
	v_div_fmas_f32 v17, v17, v23, v32
	v_div_fixup_f32 v26, v17, v26, v28
	v_mul_f32_e32 v17, 0xbfb8aa3b, v29
	v_exp_f32_e32 v17, v17
	v_pk_mul_f32 v[14:15], v[22:23], v[14:15] op_sel_hi:[0,1]
	v_pk_mul_f32 v[24:25], v[24:25], v[26:27]
	v_pk_mul_f32 v[14:15], v[84:85], v[14:15]
; __device__ __forceinline__ unsigned pk2(float lo, float hi) { return f2bf(lo) | (f2bf(hi) << 16); }
; __device__ __forceinline__ float silu(float x) { return x / (1.f + __expf(-x)); }
; __global__ void __launch_bounds__(NWAVES * 64, 2) hybrid_fwd(Args args) {
;     ...
;             for (int j = 0; j < 4; ++j) { float d[8]; float ss = 0.f;
; #pragma unroll
;                 for (int e = 0; e < 4; ++e) { const float d0 = bflo(a[j][e]) - lam * bflo(b[j][e]), d1 = bfhi(a[j][e]) - lam * bfhi(b[j][e]); d[2 * e] = d0; d[2 * e + 1] = d1; ss += d0 * d0 + d1 * d1; }
;                 ss += __shfl_xor(ss, 1); ss += __shfl_xor(ss, 2); ss += __shfl_xor(ss, 4); ss += __shfl_xor(ss, 8); ss += __shfl_xor(ss, 16);
;                 const float rstd = (1.f - LAMBDA_INIT) / sqrtf(ss * (1.f / 256.f) + RMS_EPS); v4u o;
; #pragma unroll
;                 for (int e = 0; e < 4; ++e) { const f32x4 s4 = (e >> 1) ? sl1 : sl0;
;                     o[e] = pk2(d[2 * e] * rstd * s4[(e & 1) * 2] * silu(bflo(gt[j][e])), d[2 * e + 1] * rstd * s4[(e & 1) * 2 + 1] * silu(bfhi(gt[j][e]))); }
;                 po[64 * j] = o;
;                 v4u o2;
; #pragma unroll
;                 for (int e = 0; e < 4; ++e) o2[e] = pk2(bflo(ab[j][e]) * silu(bflo(gm[j][e])), bfhi(ab[j][e]) * silu(bfhi(gm[j][e])));
;                 po[256 + 64 * j] = o2; }
	v_pk_add_f32 v[16:17], v[16:17], 1.0 op_sel_hi:[1,0]
	s_nop 0
	v_div_scale_f32 v22, s[2:3], v17, v17, v29
	v_rcp_f32_e32 v23, v22
	s_nop 0
	v_fma_f32 v26, -v22, v23, 1.0
	v_fmac_f32_e32 v23, v26, v23
	v_div_scale_f32 v26, vcc, v29, v17, v29
	v_mul_f32_e32 v27, v26, v23
	v_fma_f32 v28, -v22, v27, v26
	v_fmac_f32_e32 v27, v28, v23
	v_fma_f32 v22, -v22, v27, v26
	v_div_fmas_f32 v22, v22, v23, v27
	v_div_fixup_f32 v17, v22, v17, v29
	v_div_scale_f32 v22, s[2:3], v16, v16, v30
	v_rcp_f32_e32 v23, v22
	s_nop 0
	v_fma_f32 v26, -v22, v23, 1.0
	v_fmac_f32_e32 v23, v26, v23
	v_div_scale_f32 v26, vcc, v30, v16, v30
	v_mul_f32_e32 v27, v26, v23
	v_fma_f32 v28, -v22, v27, v26
	v_fmac_f32_e32 v27, v28, v23
	v_fma_f32 v22, -v22, v27, v26
	v_div_fmas_f32 v22, v22, v23, v27
	v_div_fixup_f32 v16, v22, v16, v30
	v_pk_mul_f32 v[14:15], v[14:15], v[16:17]
	v_bfe_u32 v22, v21, 16, 1
	v_bfe_u32 v16, v15, 16, 1
	v_bfe_u32 v17, v14, 16, 1
	v_bfe_u32 v23, v20, 16, 1
	v_add3_u32 v20, v20, v23, s24
	v_add3_u32 v21, v21, v22, s24
	v_add3_u32 v14, v14, v17, s24
	v_add3_u32 v15, v15, v16, s24
	v_bfe_u32 v16, v18, 16, 1
	v_bfe_u32 v17, v19, 16, 1
	v_bfe_u32 v22, v24, 16, 1
	v_bfe_u32 v23, v25, 16, 1
	v_add3_u32 v23, v25, v23, s24
	v_add3_u32 v22, v24, v22, s24
	v_add3_u32 v17, v19, v17, s24
	v_add3_u32 v16, v18, v16, s24
	v_lshrrev_b32_e32 v18, 16, v16
	v_lshrrev_b32_e32 v19, 16, v17
	v_lshrrev_b32_e32 v16, 16, v22
	v_lshrrev_b32_e32 v17, 16, v23
	v_and_or_b32 v17, v15, s21, v17
	v_and_or_b32 v16, v14, s21, v16
	v_and_or_b32 v15, v21, s21, v19
	v_and_or_b32 v14, v20, s21, v18
	global_store_dwordx4 v[80:81], v[14:17], off offset:3072
	s_waitcnt vmcnt(7)
	v_lshlrev_b32_e32 v18, 16, v10
	v_and_b32_e32 v20, 0xffff0000, v10
	v_lshlrev_b32_e32 v17, 16, v11
	v_mul_f32_e32 v14, 0xbfb8aa3b, v18
	v_mul_f32_e32 v15, 0xbfb8aa3b, v17
	v_exp_f32_e32 v14, v14
	v_exp_f32_e32 v15, v15
	v_mul_f32_e32 v10, 0xbfb8aa3b, v20
	v_and_b32_e32 v19, 0xffff0000, v11
	v_exp_f32_e32 v16, v10
	v_pk_add_f32 v[14:15], v[14:15], 1.0 op_sel_hi:[1,0]
	v_lshlrev_b32_e32 v11, 16, v7
	v_div_scale_f32 v21, s[2:3], v15, v15, v17
	v_rcp_f32_e32 v22, v21
	v_lshlrev_b32_e32 v10, 16, v6
	v_and_b32_e32 v7, 0xffff0000, v7
	v_and_b32_e32 v6, 0xffff0000, v6
	v_fma_f32 v23, -v21, v22, 1.0
	v_fmac_f32_e32 v22, v23, v22
	v_div_scale_f32 v23, vcc, v17, v15, v17
	v_mul_f32_e32 v24, v23, v22
	v_fma_f32 v25, -v21, v24, v23
	v_fmac_f32_e32 v24, v25, v22
	v_fma_f32 v21, -v21, v24, v23
	v_div_fmas_f32 v21, v21, v22, v24
	v_div_fixup_f32 v15, v21, v15, v17
	v_div_scale_f32 v17, s[2:3], v14, v14, v18
	v_rcp_f32_e32 v21, v17
	s_nop 0
	v_fma_f32 v22, -v17, v21, 1.0
	v_fmac_f32_e32 v21, v22, v21
	v_div_scale_f32 v22, vcc, v18, v14, v18
	v_mul_f32_e32 v23, v22, v21
	v_fma_f32 v24, -v17, v23, v22
	v_fmac_f32_e32 v23, v24, v21
	v_fma_f32 v17, -v17, v23, v22
	v_div_fmas_f32 v17, v17, v21, v23
	v_div_fixup_f32 v14, v17, v14, v18
	v_pk_mul_f32 v[10:11], v[14:15], v[10:11]
	v_mul_f32_e32 v14, 0xbfb8aa3b, v19
	v_exp_f32_e32 v17, v14
	s_nop 0
	v_pk_add_f32 v[14:15], v[16:17], 1.0 op_sel_hi:[1,0]
	s_nop 0
	v_div_scale_f32 v16, s[2:3], v15, v15, v19
	v_rcp_f32_e32 v17, v16
	s_nop 0
	v_fma_f32 v18, -v16, v17, 1.0
	v_fmac_f32_e32 v17, v18, v17
	v_div_scale_f32 v18, vcc, v19, v15, v19
	v_mul_f32_e32 v21, v18, v17
	v_fma_f32 v22, -v16, v21, v18
	v_fmac_f32_e32 v21, v22, v17
	v_fma_f32 v16, -v16, v21, v18
	v_div_fmas_f32 v16, v16, v17, v21
	v_div_fixup_f32 v15, v16, v15, v19
	v_div_scale_f32 v16, s[2:3], v14, v14, v20
	v_rcp_f32_e32 v17, v16
	s_nop 0
	v_fma_f32 v18, -v16, v17, 1.0
	v_fmac_f32_e32 v17, v18, v17
	v_div_scale_f32 v18, vcc, v20, v14, v20
	v_mul_f32_e32 v19, v18, v17
	v_fma_f32 v21, -v16, v19, v18
	v_fmac_f32_e32 v19, v21, v17
	v_fma_f32 v16, -v16, v19, v18
	v_div_fmas_f32 v16, v16, v17, v19
	v_div_fixup_f32 v14, v16, v14, v20
	v_pk_mul_f32 v[6:7], v[14:15], v[6:7]
	v_lshlrev_b32_e32 v15, 16, v13
	v_lshlrev_b32_e32 v20, 16, v12
	v_mul_f32_e32 v14, 0xbfb8aa3b, v20
	v_mul_f32_e32 v19, 0xbfb8aa3b, v15
	v_exp_f32_e32 v18, v14
	v_exp_f32_e32 v19, v19
	v_and_b32_e32 v17, 0xffff0000, v13
	v_and_b32_e32 v16, 0xffff0000, v12
	v_mul_f32_e32 v12, 0xbfb8aa3b, v16
	v_pk_add_f32 v[18:19], v[18:19], 1.0 op_sel_hi:[1,0]
	v_exp_f32_e32 v14, v12
	v_div_scale_f32 v21, s[2:3], v19, v19, v15
	v_rcp_f32_e32 v22, v21
	v_lshlrev_b32_e32 v13, 16, v9
	v_lshlrev_b32_e32 v12, 16, v8
	v_and_b32_e32 v9, 0xffff0000, v9
	v_fma_f32 v23, -v21, v22, 1.0
	v_fmac_f32_e32 v22, v23, v22
	v_div_scale_f32 v23, vcc, v15, v19, v15
	v_mul_f32_e32 v24, v23, v22
	v_fma_f32 v25, -v21, v24, v23
	v_fmac_f32_e32 v24, v25, v22
	v_fma_f32 v21, -v21, v24, v23
	v_div_fmas_f32 v21, v21, v22, v24
	v_div_fixup_f32 v19, v21, v19, v15
	v_div_scale_f32 v15, s[2:3], v18, v18, v20
	v_rcp_f32_e32 v21, v15
	v_and_b32_e32 v8, 0xffff0000, v8
	v_fma_f32 v22, -v15, v21, 1.0
	v_fmac_f32_e32 v21, v22, v21
	v_div_scale_f32 v22, vcc, v20, v18, v20
	v_mul_f32_e32 v23, v22, v21
	v_fma_f32 v24, -v15, v23, v22
	v_fmac_f32_e32 v23, v24, v21
	v_fma_f32 v15, -v15, v23, v22
	v_div_fmas_f32 v15, v15, v21, v23
	v_div_fixup_f32 v18, v15, v18, v20
	v_mul_f32_e32 v15, 0xbfb8aa3b, v17
	v_exp_f32_e32 v15, v15
	v_pk_mul_f32 v[12:13], v[18:19], v[12:13]
	v_pk_add_f32 v[14:15], v[14:15], 1.0 op_sel_hi:[1,0]
	s_nop 0
	v_div_scale_f32 v18, s[2:3], v15, v15, v17
	v_rcp_f32_e32 v19, v18
	s_nop 0
	v_fma_f32 v20, -v18, v19, 1.0
	v_fmac_f32_e32 v19, v20, v19
	v_div_scale_f32 v20, vcc, v17, v15, v17
	v_mul_f32_e32 v21, v20, v19
	v_fma_f32 v22, -v18, v21, v20
	v_fmac_f32_e32 v21, v22, v19
	v_fma_f32 v18, -v18, v21, v20
	v_div_fmas_f32 v18, v18, v19, v21
	v_div_fixup_f32 v15, v18, v15, v17
	v_div_scale_f32 v17, s[2:3], v14, v14, v16
	v_rcp_f32_e32 v18, v17
	s_nop 0
	v_fma_f32 v19, -v17, v18, 1.0
	v_fmac_f32_e32 v18, v19, v18
	v_div_scale_f32 v19, vcc, v16, v14, v16
	v_mul_f32_e32 v20, v19, v18
	v_fma_f32 v21, -v17, v20, v19
	v_fmac_f32_e32 v20, v21, v18
	v_fma_f32 v17, -v17, v20, v19
	v_div_fmas_f32 v17, v17, v18, v20
	v_div_fixup_f32 v14, v17, v14, v16
	v_pk_mul_f32 v[8:9], v[14:15], v[8:9]
	v_bfe_u32 v16, v7, 16, 1
	v_bfe_u32 v14, v9, 16, 1
	v_bfe_u32 v15, v8, 16, 1
	v_bfe_u32 v17, v6, 16, 1
	v_add3_u32 v6, v6, v17, s24
	v_add3_u32 v7, v7, v16, s24
	v_add3_u32 v8, v8, v15, s24
	v_add3_u32 v9, v9, v14, s24
	v_bfe_u32 v14, v10, 16, 1
	v_bfe_u32 v15, v11, 16, 1
	v_bfe_u32 v16, v12, 16, 1
	v_bfe_u32 v17, v13, 16, 1
	v_add3_u32 v13, v13, v17, s24
	v_add3_u32 v12, v12, v16, s24
	v_add3_u32 v11, v11, v15, s24
	v_add3_u32 v10, v10, v14, s24
	v_lshrrev_b32_e32 v10, 16, v10
	v_lshrrev_b32_e32 v11, 16, v11
	v_lshrrev_b32_e32 v12, 16, v12
	v_lshrrev_b32_e32 v13, 16, v13
	v_and_or_b32 v9, v9, s21, v13
	v_and_or_b32 v8, v8, s21, v12
	v_and_or_b32 v7, v7, s21, v11
	v_and_or_b32 v6, v6, s21, v10
	global_store_dwordx4 v[78:79], v[6:9], off offset:3072
	s_cbranch_scc1 .LBB0_847

; #define lane lane_id()
; __global__ void __launch_bounds__(NWAVES * 64, 2) hybrid_fwd(Args args) {
;     ...
;         for (int m = gw; m < MR; m += NGW) {
;             const v4u* yr = (const v4u*)(Y16 + (size_t)m * D_MODEL) + lane; f32x4* orow = (f32x4*)(out + (size_t)m * D_MODEL) + 2 * lane;
;             const f32x4* xr = (const f32x4*)(x + (size_t)m * D_MODEL) + 2 * lane; const f32x4* gr = (const f32x4*)g_post + 2 * lane;
;             v4u v[8]; float s = 0.f;
; #pragma unroll
;             for (int j = 0; j < 8; ++j) { v[j] = yr[64 * j];
; #pragma unroll
;                 for (int e = 0; e < 4; ++e) { const float a = bflo(v[j][e]), b = bfhi(v[j][e]); s += a * a + b * b; } }
;             const float rstd = 1.f / sqrtf(wave_sum(s) * (1.f / D_MODEL) + RMS_EPS);
.LBB0_977:
	s_cmp_lt_i32 s30, 8
	s_cselect_b64 s[0:1], -1, 0
	s_and_b64 s[0:1], s[0:1], s[2:3]
	s_cmpk_lt_i32 s34, 0x4000
	s_cselect_b64 s[2:3], -1, 0
	s_and_b64 s[0:1], s[0:1], s[2:3]
	s_andn2_b64 vcc, exec, s[0:1]
	s_cbranch_vccnz .LBB0_980
	s_ashr_i32 s35, s34, 31
	s_lshl_b64 s[0:1], s[34:35], 13
	s_add_u32 s0, s28, s0
	s_addc_u32 s1, s29, s1
	s_add_u32 s2, s0, 0x11301c00
	s_waitcnt vmcnt(0)
	v_mbcnt_hi_u32_b32 v31, -1, v146
	s_addc_u32 s3, s1, 0
	s_ashr_i32 s69, s68, 31
	v_and_b32_e32 v0, 64, v31
	s_lshl_b64 s[4:5], s[68:69], 13
	s_lshl_b64 s[6:7], s[34:35], 14
	s_lshl_b64 s[8:9], s[68:69], 14
	s_movk_i32 s24, 0xf000
	v_add_u32_e32 v58, 64, v0
	v_xor_b32_e32 v59, 1, v31
	v_xor_b32_e32 v60, 2, v31
	v_xor_b32_e32 v61, 4, v31
	v_xor_b32_e32 v62, 8, v31
	v_xor_b32_e32 v63, 16, v31
	v_xor_b32_e32 v64, 32, v31
	v_mov_b32_e32 v65, 0x358637bd
	s_mov_b32 s25, 0xf800000
	v_mov_b32_e32 v66, 0x260
	s_mov_b64 s[10:11], 0x1000
	s_movk_i32 s26, 0x1000
	s_mov_b64 s[14:15], 0x1800
	s_mov_b64 s[16:17], 0x2000
	s_movk_i32 s27, 0x2000
	s_mov_b64 s[18:19], 0x2800
	s_mov_b64 s[20:21], 0x3000
	s_movk_i32 s28, 0x3000
	s_mov_b64 s[22:23], 0x3800
.LBB0_979:
	v_cmp_lt_i32_e32 vcc, v59, v58
	v_mbcnt_lo_u32_b32 v0, -1, 0
	v_mbcnt_hi_u32_b32 v0, -1, v0
	v_mbcnt_lo_u32_b32 v2, -1, 0
	v_mbcnt_hi_u32_b32 v2, -1, v2
	s_add_u32 s0, s50, s6
	v_mbcnt_lo_u32_b32 v3, -1, 0
	v_mbcnt_hi_u32_b32 v3, -1, v3
	s_waitcnt lgkmcnt(2)
	v_ashrrev_i32_e32 v1, 31, v0
	v_cndmask_b32_e32 v5, v31, v59, vcc
	v_cmp_lt_i32_e32 vcc, v60, v58
	v_lshlrev_b32_e32 v2, 1, v2
	v_mbcnt_lo_u32_b32 v4, -1, 0
	v_mbcnt_hi_u32_b32 v4, -1, v4
	s_addc_u32 s1, s51, s7
	v_cndmask_b32_e32 v6, v31, v60, vcc
	v_cmp_lt_i32_e32 vcc, v61, v58
	v_lshlrev_b32_e32 v22, 1, v3
	v_lshl_add_u64 v[26:27], v[0:1], 4, s[2:3]
	v_cndmask_b32_e32 v7, v31, v61, vcc
	v_cmp_lt_i32_e32 vcc, v62, v58
	v_ashrrev_i32_e32 v3, 31, v2
	v_lshlrev_b32_e32 v24, 1, v4
	v_cndmask_b32_e32 v8, v31, v62, vcc
	v_cmp_lt_i32_e32 vcc, v63, v58
	v_lshlrev_b32_e32 v30, 2, v5
	v_lshl_add_u64 v[4:5], v[2:3], 4, s[0:1]
	s_waitcnt lgkmcnt(1)
	v_cndmask_b32_e32 v9, v31, v63, vcc
	v_cmp_lt_i32_e32 vcc, v64, v58
	v_lshlrev_b32_e32 v67, 2, v6
	v_lshlrev_b32_e32 v106, 2, v7
	v_cndmask_b32_e32 v10, v31, v64, vcc
	v_add_co_u32_e32 v2, vcc, s24, v26
	v_lshlrev_b32_e32 v107, 2, v8
	s_nop 0
	v_addc_co_u32_e32 v3, vcc, -1, v27, vcc
	v_lshlrev_b32_e32 v108, 2, v9
	v_lshlrev_b32_e32 v109, 2, v10
	global_load_dwordx4 v[6:9], v[26:27], off offset:-4096
	s_waitcnt lgkmcnt(0)
	global_load_dwordx4 v[10:13], v[26:27], off offset:-3072
	global_load_dwordx4 v[14:17], v[26:27], off offset:-2048
	global_load_dwordx4 v[18:21], v[26:27], off offset:-1024
	global_load_dwordx4 v[48:51], v[2:3], off offset:-3072
	global_load_dwordx4 v[52:55], v[2:3], off offset:-2048
	global_load_dwordx4 v[68:71], v[2:3], off offset:-1024
	global_load_dwordx4 v[72:75], v[26:27], off
	v_ashrrev_i32_e32 v25, 31, v24
	s_add_u32 s30, s12, s6
	v_ashrrev_i32_e32 v23, 31, v22
	s_addc_u32 s31, s13, s7
	v_lshl_add_u64 v[0:1], v[24:25], 4, s[48:49]
	v_lshl_add_u64 v[2:3], v[22:23], 4, s[30:31]
	global_load_dwordx4 v[76:79], v[0:1], off offset:16
	global_load_dwordx4 v[80:83], v[0:1], off
	global_load_dwordx4 v[84:87], v[2:3], off offset:16 nt
	global_load_dwordx4 v[88:91], v[2:3], off nt
	s_add_i32 s34, s34, s68
	s_add_u32 s2, s2, s4
	s_addc_u32 s3, s3, s5
	s_add_u32 s50, s50, s8
	s_addc_u32 s51, s51, s9
	s_add_u32 s12, s12, s8
	s_addc_u32 s13, s13, s9
	s_cmpk_lt_i32 s34, 0x4000
	s_waitcnt vmcnt(11)
	v_lshlrev_b32_e32 v40, 16, v6
	s_waitcnt vmcnt(7)
	v_and_b32_e32 v93, 0xffff0000, v48
	v_and_b32_e32 v95, 0xffff0000, v49
	v_and_b32_e32 v41, 0xffff0000, v6
	v_lshlrev_b32_e32 v44, 16, v7
	v_and_b32_e32 v45, 0xffff0000, v7
	v_lshlrev_b32_e32 v32, 16, v10
	v_and_b32_e32 v33, 0xffff0000, v10
	v_lshlrev_b32_e32 v36, 16, v11
	v_and_b32_e32 v37, 0xffff0000, v11
	v_lshlrev_b32_e32 v92, 16, v48
	v_lshlrev_b32_e32 v94, 16, v49
	v_and_b32_e32 v97, 0xffff0000, v50
	s_waitcnt vmcnt(4)
	v_lshlrev_b32_e32 v6, 16, v72
	v_and_b32_e32 v7, 0xffff0000, v72
	v_lshlrev_b32_e32 v10, 16, v73
	v_and_b32_e32 v11, 0xffff0000, v73
	v_mul_f32_e32 v72, v93, v93
	v_mul_f32_e32 v73, v95, v95
	v_lshlrev_b32_e32 v42, 16, v8
	v_and_b32_e32 v43, 0xffff0000, v8
	v_lshlrev_b32_e32 v34, 16, v12
	v_and_b32_e32 v35, 0xffff0000, v12
	v_lshlrev_b32_e32 v96, 16, v50
	v_and_b32_e32 v99, 0xffff0000, v51
	v_lshlrev_b32_e32 v8, 16, v74
	v_and_b32_e32 v12, 0xffff0000, v74
	v_mul_f32_e32 v74, v97, v97
	v_fmac_f32_e32 v72, v92, v92
	v_fmac_f32_e32 v73, v94, v94
	v_lshlrev_b32_e32 v46, 16, v9
	v_and_b32_e32 v47, 0xffff0000, v9
	v_lshlrev_b32_e32 v38, 16, v13
	v_and_b32_e32 v39, 0xffff0000, v13
	v_lshlrev_b32_e32 v98, 16, v51
	v_and_b32_e32 v57, 0xffff0000, v52
	v_lshlrev_b32_e32 v9, 16, v75
	v_and_b32_e32 v13, 0xffff0000, v75
	v_mul_f32_e32 v75, v99, v99
	v_fmac_f32_e32 v74, v96, v96
	v_add_f32_e32 v72, v72, v73
	v_lshlrev_b32_e32 v56, 16, v52
	v_and_b32_e32 v101, 0xffff0000, v53
	v_mul_f32_e32 v124, v57, v57
	v_fmac_f32_e32 v75, v98, v98
	v_add_f32_e32 v72, v72, v74
	v_lshlrev_b32_e32 v100, 16, v53
	v_and_b32_e32 v103, 0xffff0000, v54
	v_mul_f32_e32 v125, v101, v101
	v_fmac_f32_e32 v124, v56, v56
	v_add_f32_e32 v72, v72, v75
	v_lshlrev_b32_e32 v102, 16, v54
	v_and_b32_e32 v105, 0xffff0000, v55
	v_mul_f32_e32 v126, v103, v103
	v_fmac_f32_e32 v125, v100, v100
	v_add_f32_e32 v72, v72, v124
	v_lshlrev_b32_e32 v104, 16, v55
	v_and_b32_e32 v49, 0xffff0000, v68
	v_mul_f32_e32 v127, v105, v105
	v_fmac_f32_e32 v126, v102, v102
	v_add_f32_e32 v72, v72, v125
	v_lshlrev_b32_e32 v48, 16, v68
	v_and_b32_e32 v53, 0xffff0000, v69
	v_mul_f32_e32 v128, v49, v49
; __global__ void __launch_bounds__(NWAVES * 64, 2) hybrid_fwd(Args args) {
;     ...
;             for (int j = 0; j < 8; ++j) { v[j] = yr[64 * j];
; #pragma unroll
;                 for (int e = 0; e < 4; ++e) { const float a = bflo(v[j][e]), b = bfhi(v[j][e]); s += a * a + b * b; } }
;             const float rstd = 1.f / sqrtf(wave_sum(s) * (1.f / D_MODEL) + RMS_EPS);
; #pragma unroll
;             for (int j = 0; j < 8; ++j) { const f32x4 g0 = gr[128 * j], g1 = gr[128 * j + 1], x0 = __builtin_nontemporal_load(xr + 128 * j), x1 = __builtin_nontemporal_load(xr + 128 * j + 1);
;                 f32x4 y0 = {bflo(v[j][0]), bfhi(v[j][0]), bflo(v[j][1]), bfhi(v[j][1])}, y1 = {bflo(v[j][2]), bfhi(v[j][2]), bflo(v[j][3]), bfhi(v[j][3])};
;                 __builtin_nontemporal_store(x0 + y0 * rstd * g0, orow + 128 * j); __builtin_nontemporal_store(x1 + y1 * rstd * g1, orow + 128 * j + 1); }
	v_fmac_f32_e32 v127, v104, v104
	v_add_f32_e32 v72, v72, v126
	v_lshlrev_b32_e32 v52, 16, v69
	v_and_b32_e32 v51, 0xffff0000, v70
	v_mul_f32_e32 v129, v53, v53
	v_fmac_f32_e32 v128, v48, v48
	v_add_f32_e32 v72, v72, v127
	v_lshlrev_b32_e32 v50, 16, v70
	v_and_b32_e32 v55, 0xffff0000, v71
	v_mul_f32_e32 v130, v51, v51
	v_fmac_f32_e32 v129, v52, v52
	v_add_f32_e32 v72, v72, v128
	v_lshlrev_b32_e32 v54, 16, v71
	v_mul_f32_e32 v131, v55, v55
	v_fmac_f32_e32 v130, v50, v50
	v_add_f32_e32 v72, v72, v129
	v_mul_f32_e32 v70, v41, v41
	v_fmac_f32_e32 v131, v54, v54
	v_add_f32_e32 v72, v72, v130
	v_mul_f32_e32 v71, v45, v45
	v_fmac_f32_e32 v70, v40, v40
	v_add_f32_e32 v72, v72, v131
	v_mul_f32_e32 v110, v43, v43
	v_fmac_f32_e32 v71, v44, v44
	v_add_f32_e32 v70, v72, v70
	v_mul_f32_e32 v111, v47, v47
	v_fmac_f32_e32 v110, v42, v42
	v_add_f32_e32 v70, v70, v71
	v_mul_f32_e32 v112, v33, v33
	v_fmac_f32_e32 v111, v46, v46
	v_add_f32_e32 v70, v70, v110
	v_mul_f32_e32 v113, v37, v37
	v_fmac_f32_e32 v112, v32, v32
	v_add_f32_e32 v70, v70, v111
	v_mul_f32_e32 v114, v35, v35
	v_fmac_f32_e32 v113, v36, v36
	v_add_f32_e32 v70, v70, v112
	v_and_b32_e32 v23, 0xffff0000, v14
	v_mul_f32_e32 v115, v39, v39
	v_fmac_f32_e32 v114, v34, v34
	v_add_f32_e32 v70, v70, v113
	v_lshlrev_b32_e32 v22, 16, v14
	v_and_b32_e32 v27, 0xffff0000, v15
	v_mul_f32_e32 v116, v23, v23
	v_fmac_f32_e32 v115, v38, v38
	v_add_f32_e32 v70, v70, v114
	v_lshlrev_b32_e32 v26, 16, v15
	v_and_b32_e32 v25, 0xffff0000, v16
	v_mul_f32_e32 v117, v27, v27
	v_fmac_f32_e32 v116, v22, v22
	v_add_f32_e32 v70, v70, v115
	v_lshlrev_b32_e32 v24, 16, v16
	v_and_b32_e32 v29, 0xffff0000, v17
	v_mul_f32_e32 v118, v25, v25
	v_fmac_f32_e32 v117, v26, v26
	v_add_f32_e32 v70, v70, v116
	v_lshlrev_b32_e32 v28, 16, v17
	v_and_b32_e32 v15, 0xffff0000, v18
	v_mul_f32_e32 v119, v29, v29
	v_fmac_f32_e32 v118, v24, v24
	v_add_f32_e32 v70, v70, v117
	v_lshlrev_b32_e32 v14, 16, v18
	v_lshlrev_b32_e32 v18, 16, v19
	v_and_b32_e32 v19, 0xffff0000, v19
	v_mul_f32_e32 v120, v15, v15
	v_fmac_f32_e32 v119, v28, v28
	v_add_f32_e32 v70, v70, v118
	v_and_b32_e32 v17, 0xffff0000, v20
	v_mul_f32_e32 v121, v19, v19
	v_fmac_f32_e32 v120, v14, v14
	v_add_f32_e32 v70, v70, v119
	v_lshlrev_b32_e32 v16, 16, v20
	v_lshlrev_b32_e32 v20, 16, v21
	v_and_b32_e32 v21, 0xffff0000, v21
	v_mul_f32_e32 v122, v17, v17
	v_fmac_f32_e32 v121, v18, v18
	v_add_f32_e32 v70, v70, v120
	v_mul_f32_e32 v123, v21, v21
	v_fmac_f32_e32 v122, v16, v16
	v_add_f32_e32 v70, v70, v121
	v_fmac_f32_e32 v123, v20, v20
	v_mul_f32_e32 v132, v7, v7
	v_add_f32_e32 v70, v70, v122
	v_mul_f32_e32 v133, v11, v11
	v_fmac_f32_e32 v132, v6, v6
	v_add_f32_e32 v70, v70, v123
	v_pk_mul_f32 v[68:69], v[12:13], v[12:13]
	v_fmac_f32_e32 v133, v10, v10
	v_add_f32_e32 v70, v70, v132
	v_pk_fma_f32 v[68:69], v[8:9], v[8:9], v[68:69]
	v_add_f32_e32 v70, v70, v133
	v_add_f32_e32 v68, v70, v68
	v_add_f32_e32 v68, v68, v69
	ds_bpermute_b32 v30, v30, v68
	s_waitcnt lgkmcnt(0)
	v_add_f32_e32 v30, v68, v30
	ds_bpermute_b32 v67, v67, v30
	s_waitcnt lgkmcnt(0)
	v_add_f32_e32 v30, v30, v67
	ds_bpermute_b32 v67, v106, v30
	s_waitcnt lgkmcnt(0)
	v_add_f32_e32 v30, v30, v67
	ds_bpermute_b32 v67, v107, v30
	s_waitcnt lgkmcnt(0)
	v_add_f32_e32 v30, v30, v67
	ds_bpermute_b32 v67, v108, v30
	s_waitcnt lgkmcnt(0)
	v_add_f32_e32 v30, v30, v67
	ds_bpermute_b32 v67, v109, v30
	s_waitcnt lgkmcnt(0)
	v_add_f32_e32 v30, v30, v67
	v_fmamk_f32 v30, v30, 0x39800000, v65
	v_mul_f32_e32 v67, 0x4f800000, v30
	v_cmp_gt_f32_e32 vcc, s25, v30
	s_nop 1
	v_cndmask_b32_e32 v30, v30, v67, vcc
	v_sqrt_f32_e32 v67, v30
	s_nop 0
	v_add_u32_e32 v68, -1, v67
	v_add_u32_e32 v69, 1, v67
	v_fma_f32 v70, -v68, v67, v30
	v_fma_f32 v71, -v69, v67, v30
	v_cmp_ge_f32_e64 s[0:1], 0, v70
	s_nop 1
	v_cndmask_b32_e64 v67, v67, v68, s[0:1]
	v_cmp_lt_f32_e64 s[0:1], 0, v71
	s_nop 1
	v_cndmask_b32_e64 v67, v67, v69, s[0:1]
	v_mul_f32_e32 v68, 0x37800000, v67
	v_cndmask_b32_e32 v67, v67, v68, vcc
	v_cmp_class_f32_e32 vcc, v30, v66
	s_nop 1
	v_cndmask_b32_e32 v30, v67, v30, vcc
	v_div_scale_f32 v67, s[0:1], v30, v30, 1.0
	v_rcp_f32_e32 v69, v67
	v_div_scale_f32 v68, vcc, 1.0, v30, 1.0
	v_fma_f32 v70, -v67, v69, 1.0
	v_fmac_f32_e32 v69, v70, v69
	v_mul_f32_e32 v70, v68, v69
	v_fma_f32 v71, -v67, v70, v68
	v_fmac_f32_e32 v70, v71, v69
	v_fma_f32 v67, -v67, v70, v68
	v_div_fmas_f32 v67, v67, v69, v70
	v_div_fixup_f32 v30, v67, v30, 1.0
	v_pk_mul_f32 v[68:69], v[30:31], v[92:93] op_sel_hi:[0,1]
	v_pk_mul_f32 v[70:71], v[30:31], v[94:95] op_sel_hi:[0,1]
	v_pk_mul_f32 v[72:73], v[30:31], v[96:97] op_sel_hi:[0,1]
	v_pk_mul_f32 v[74:75], v[30:31], v[98:99] op_sel_hi:[0,1]
	s_waitcnt vmcnt(0)
	v_pk_fma_f32 v[70:71], v[70:71], v[82:83], v[90:91]
	v_pk_fma_f32 v[68:69], v[68:69], v[80:81], v[88:89]
	v_pk_fma_f32 v[74:75], v[74:75], v[78:79], v[86:87]
	v_pk_fma_f32 v[72:73], v[72:73], v[76:77], v[84:85]
	global_store_dwordx4 v[4:5], v[68:71], off nt
	global_store_dwordx4 v[4:5], v[72:75], off offset:16 nt
	global_load_dwordx4 v[68:71], v[2:3], off offset:2048 nt
	s_nop 0
	global_load_dwordx4 v[72:75], v[0:1], off offset:2048
	global_load_dwordx4 v[76:79], v[0:1], off offset:2064
	global_load_dwordx4 v[80:83], v[2:3], off offset:2064 nt
	v_add_co_u32_e32 v86, vcc, s27, v0
	v_pk_mul_f32 v[92:93], v[30:31], v[100:101] op_sel_hi:[0,1]
	v_pk_mul_f32 v[56:57], v[30:31], v[56:57] op_sel_hi:[0,1]
	v_addc_co_u32_e32 v87, vcc, 0, v1, vcc
	v_pk_mul_f32 v[94:95], v[30:31], v[104:105] op_sel_hi:[0,1]
	v_pk_mul_f32 v[96:97], v[30:31], v[102:103] op_sel_hi:[0,1]
	v_add_co_u32_e32 v90, vcc, s27, v2
	v_lshl_add_u64 v[84:85], v[0:1], 0, s[10:11]
	v_lshl_add_u64 v[88:89], v[2:3], 0, s[10:11]
	v_addc_co_u32_e32 v91, vcc, 0, v3, vcc
	v_pk_mul_f32 v[52:53], v[30:31], v[52:53] op_sel_hi:[0,1]
	v_pk_mul_f32 v[48:49], v[30:31], v[48:49] op_sel_hi:[0,1]
	v_pk_mul_f32 v[54:55], v[30:31], v[54:55] op_sel_hi:[0,1]
	v_pk_mul_f32 v[98:99], v[30:31], v[50:51] op_sel_hi:[0,1]
	v_pk_mul_f32 v[44:45], v[30:31], v[44:45] op_sel_hi:[0,1]
	v_pk_mul_f32 v[40:41], v[30:31], v[40:41] op_sel_hi:[0,1]
	v_pk_mul_f32 v[46:47], v[30:31], v[46:47] op_sel_hi:[0,1]
	v_pk_mul_f32 v[36:37], v[30:31], v[36:37] op_sel_hi:[0,1]
	v_pk_mul_f32 v[32:33], v[30:31], v[32:33] op_sel_hi:[0,1]
	v_pk_mul_f32 v[38:39], v[30:31], v[38:39] op_sel_hi:[0,1]
	v_pk_mul_f32 v[26:27], v[30:31], v[26:27] op_sel_hi:[0,1]
	v_pk_mul_f32 v[22:23], v[30:31], v[22:23] op_sel_hi:[0,1]
	v_pk_mul_f32 v[28:29], v[30:31], v[28:29] op_sel_hi:[0,1]
	v_pk_mul_f32 v[10:11], v[30:31], v[10:11] op_sel_hi:[0,1]
	v_pk_mul_f32 v[6:7], v[30:31], v[6:7] op_sel_hi:[0,1]
	s_waitcnt vmcnt(2)
; __global__ void __launch_bounds__(NWAVES * 64, 2) hybrid_fwd(Args args) {
;     ...
; #pragma unroll
;             for (int j = 0; j < 8; ++j) { const f32x4 g0 = gr[128 * j], g1 = gr[128 * j + 1], x0 = __builtin_nontemporal_load(xr + 128 * j), x1 = __builtin_nontemporal_load(xr + 128 * j + 1);
;                 f32x4 y0 = {bflo(v[j][0]), bfhi(v[j][0]), bflo(v[j][1]), bfhi(v[j][1])}, y1 = {bflo(v[j][2]), bfhi(v[j][2]), bflo(v[j][3]), bfhi(v[j][3])};
;                 __builtin_nontemporal_store(x0 + y0 * rstd * g0, orow + 128 * j); __builtin_nontemporal_store(x1 + y1 * rstd * g1, orow + 128 * j + 1); }
	v_pk_fma_f32 v[68:69], v[56:57], v[72:73], v[68:69]
	v_pk_fma_f32 v[70:71], v[92:93], v[74:75], v[70:71]
	s_waitcnt vmcnt(0)
	v_pk_fma_f32 v[72:73], v[96:97], v[76:77], v[80:81]
	v_pk_fma_f32 v[74:75], v[94:95], v[78:79], v[82:83]
	global_store_dwordx4 v[4:5], v[68:71], off offset:2048 nt
	global_store_dwordx4 v[4:5], v[72:75], off offset:2064 nt
	global_load_dwordx4 v[68:71], v[86:87], off offset:-4096
	s_nop 0
	global_load_dwordx4 v[72:75], v[90:91], off offset:-4096 nt
	global_load_dwordx4 v[76:79], v[84:85], off offset:16
	global_load_dwordx4 v[80:83], v[88:89], off offset:16 nt
	v_add_co_u32_e32 v56, vcc, s26, v0
	v_lshl_add_u64 v[92:93], v[0:1], 0, s[14:15]
	s_nop 0
	v_addc_co_u32_e32 v57, vcc, 0, v1, vcc
	v_add_co_u32_e32 v84, vcc, s26, v4
	v_lshl_add_u64 v[96:97], v[2:3], 0, s[14:15]
	s_nop 0
	v_addc_co_u32_e32 v85, vcc, 0, v5, vcc
	v_add_co_u32_e32 v88, vcc, s27, v4
	s_waitcnt vmcnt(2)
	v_pk_fma_f32 v[48:49], v[48:49], v[68:69], v[72:73]
	v_addc_co_u32_e32 v89, vcc, 0, v5, vcc
	v_pk_fma_f32 v[50:51], v[52:53], v[70:71], v[74:75]
	v_add_co_u32_e32 v94, vcc, s26, v2
	s_waitcnt vmcnt(0)
	v_pk_fma_f32 v[52:53], v[98:99], v[76:77], v[80:81]
	v_pk_fma_f32 v[54:55], v[54:55], v[78:79], v[82:83]
	global_store_dwordx4 v[88:89], v[48:51], off offset:-4096 nt
	global_store_dwordx4 v[84:85], v[52:55], off offset:16 nt
	v_addc_co_u32_e32 v95, vcc, 0, v3, vcc
	global_load_dwordx4 v[48:51], v[56:57], off offset:2048
	global_load_dwordx4 v[52:55], v[94:95], off offset:2048 nt
	global_load_dwordx4 v[68:71], v[92:93], off offset:16
	global_load_dwordx4 v[72:75], v[96:97], off offset:16 nt
	v_pk_mul_f32 v[78:79], v[30:31], v[42:43] op_sel_hi:[0,1]
	v_lshl_add_u64 v[56:57], v[0:1], 0, s[16:17]
	v_lshl_add_u64 v[76:77], v[2:3], 0, s[16:17]
	s_waitcnt vmcnt(2)
	v_pk_fma_f32 v[40:41], v[40:41], v[48:49], v[52:53]
	v_pk_fma_f32 v[42:43], v[44:45], v[50:51], v[54:55]
	s_waitcnt vmcnt(0)
	v_pk_fma_f32 v[44:45], v[78:79], v[68:69], v[72:73]
	v_pk_fma_f32 v[46:47], v[46:47], v[70:71], v[74:75]
	global_store_dwordx4 v[84:85], v[40:43], off offset:2048 nt
	global_store_dwordx4 v[84:85], v[44:47], off offset:2064 nt
	global_load_dwordx4 v[40:43], v[86:87], off
	s_nop 0
	global_load_dwordx4 v[44:47], v[90:91], off nt
	global_load_dwordx4 v[48:51], v[56:57], off offset:16
	global_load_dwordx4 v[52:55], v[76:77], off offset:16 nt
	v_pk_mul_f32 v[70:71], v[30:31], v[34:35] op_sel_hi:[0,1]
	v_lshl_add_u64 v[56:57], v[0:1], 0, s[18:19]
	v_lshl_add_u64 v[68:69], v[2:3], 0, s[18:19]
	s_waitcnt vmcnt(2)
	v_pk_fma_f32 v[32:33], v[32:33], v[40:41], v[44:45]
	v_pk_fma_f32 v[34:35], v[36:37], v[42:43], v[46:47]
	s_waitcnt vmcnt(0)
	v_pk_fma_f32 v[36:37], v[70:71], v[48:49], v[52:53]
	v_pk_fma_f32 v[38:39], v[38:39], v[50:51], v[54:55]
	global_store_dwordx4 v[88:89], v[32:35], off nt
	global_store_dwordx4 v[88:89], v[36:39], off offset:16 nt
	global_load_dwordx4 v[32:35], v[86:87], off offset:2048
	s_nop 0
	global_load_dwordx4 v[36:39], v[90:91], off offset:2048 nt
	global_load_dwordx4 v[40:43], v[56:57], off offset:16
	global_load_dwordx4 v[44:47], v[68:69], off offset:16 nt
	v_add_co_u32_e32 v50, vcc, s28, v0
	v_pk_mul_f32 v[56:57], v[30:31], v[24:25] op_sel_hi:[0,1]
	s_nop 0
	v_addc_co_u32_e32 v51, vcc, 0, v1, vcc
	v_add_co_u32_e32 v54, vcc, s28, v2
	v_lshl_add_u64 v[48:49], v[0:1], 0, s[20:21]
	s_nop 0
	v_addc_co_u32_e32 v55, vcc, 0, v3, vcc
	v_lshl_add_u64 v[52:53], v[2:3], 0, s[20:21]
	s_waitcnt vmcnt(2)
	v_pk_fma_f32 v[22:23], v[22:23], v[32:33], v[36:37]
	v_pk_fma_f32 v[24:25], v[26:27], v[34:35], v[38:39]
	s_waitcnt vmcnt(0)
	v_pk_fma_f32 v[26:27], v[56:57], v[40:41], v[44:45]
	v_pk_fma_f32 v[28:29], v[28:29], v[42:43], v[46:47]
	global_store_dwordx4 v[88:89], v[22:25], off offset:2048 nt
	global_store_dwordx4 v[88:89], v[26:29], off offset:2064 nt
	global_load_dwordx4 v[22:25], v[54:55], off nt
	s_nop 0
	global_load_dwordx4 v[26:29], v[50:51], off
	global_load_dwordx4 v[32:35], v[48:49], off offset:16
	global_load_dwordx4 v[36:39], v[52:53], off offset:16 nt
	v_add_co_u32_e32 v40, vcc, s28, v4
	v_lshl_add_u64 v[42:43], v[2:3], 0, s[22:23]
	s_nop 0
	v_addc_co_u32_e32 v41, vcc, 0, v5, vcc
	v_lshl_add_u64 v[4:5], v[0:1], 0, s[22:23]
	v_pk_mul_f32 v[2:3], v[30:31], v[18:19] op_sel_hi:[0,1]
	v_pk_mul_f32 v[0:1], v[30:31], v[14:15] op_sel_hi:[0,1]
	v_pk_mul_f32 v[18:19], v[30:31], v[20:21] op_sel_hi:[0,1]
	v_pk_mul_f32 v[14:15], v[30:31], v[16:17] op_sel_hi:[0,1]
	s_waitcnt vmcnt(2)
	v_pk_fma_f32 v[0:1], v[0:1], v[26:27], v[22:23]
	v_pk_fma_f32 v[2:3], v[2:3], v[28:29], v[24:25]
	s_waitcnt vmcnt(0)
	v_pk_fma_f32 v[14:15], v[14:15], v[32:33], v[36:37]
	v_pk_fma_f32 v[16:17], v[18:19], v[34:35], v[38:39]
	global_store_dwordx4 v[40:41], v[0:3], off nt
	global_store_dwordx4 v[40:41], v[14:17], off offset:16 nt
	global_load_dwordx4 v[0:3], v[50:51], off offset:2048
	s_nop 0
	global_load_dwordx4 v[14:17], v[54:55], off offset:2048 nt
	global_load_dwordx4 v[18:21], v[4:5], off offset:16
	global_load_dwordx4 v[22:25], v[42:43], off offset:16 nt
	v_mov_b32_e32 v4, v9
	v_mov_b32_e32 v5, v13
	v_mov_b32_e32 v9, v12
	v_pk_mul_f32 v[12:13], v[30:31], v[4:5] op_sel_hi:[0,1]
	v_pk_mul_f32 v[4:5], v[30:31], v[8:9] op_sel_hi:[0,1]
	s_waitcnt vmcnt(2)
	v_pk_fma_f32 v[0:1], v[6:7], v[0:1], v[14:15]
	v_pk_fma_f32 v[2:3], v[10:11], v[2:3], v[16:17]
	s_waitcnt vmcnt(0)
	v_pk_fma_f32 v[4:5], v[4:5], v[18:19], v[22:23]
	v_pk_fma_f32 v[6:7], v[12:13], v[20:21], v[24:25]
	global_store_dwordx4 v[40:41], v[0:3], off offset:2048 nt
	global_store_dwordx4 v[40:41], v[4:7], off offset:2064 nt
	s_cbranch_scc1 .LBB0_979
